# up-projection epilogue: conv taps via DPP row rotate instead of 128 LDS bpermutes per wave
# speedup vs baseline: 1.0028x; 1.0028x over previous
; __device__ __forceinline__ unsigned cvt_pk_bf16(float lo, float hi) { unsigned r; asm volatile("v_cvt_pk_bf16_f32 %0, %1, %2" : "=v"(r) : "v"(lo), "v"(hi)); return r; }
;     __device__ __forceinline__ void operator()(const f32x4 (&acc)[2][2][4][2], const Unit& u, int wr, int wc, int fr, int fq) const {
;     ...
;             for (int m = 0; m < 4; ++m) rs[ai][m] = __builtin_amdgcn_rsqf((float)ss[u.pm * BM + ai * HALF + wr * 64 + m * 16 + fr] * (1.f / (2048.f * 262144.f)) + 1e-6f);
; #pragma unroll
;         for (int n = 0; n < 2; ++n) {
;             const int cbase = 128 * u.pn + 32 * wc + 16 * n + 4 * fq;
;             const f32x4 w0 = *(const f32x4*)(cw + cbase), w1 = *(const f32x4*)(cw + FF + cbase), w2 = *(const f32x4*)(cw + 2 * FF + cbase), b4 = *(const f32x4*)(cb + cbase);
; #pragma unroll
;             for (int ai = 0; ai < 2; ++ai) {
;                 const int slab = u.pm * 4 + 2 * ai + wr;
;                 f32x4 r1p = (f32x4){0.f, 0.f, 0.f, 0.f}, r2p = (f32x4){0.f, 0.f, 0.f, 0.f};
; #pragma unroll
;                 for (int m = 0; m < 4; ++m) {
;                     const f32x4 g = acc[ai][1][m][n] * rs[ai][m], v = acc[ai][0][m][n] * rs[ai][m];
;                     f32x4 r1, r2, a;
; #pragma unroll
;                     for (int e = 0; e < 4; ++e) { r1[e] = __shfl(g[e], src1); r2[e] = __shfl(g[e], src2); }
; #pragma unroll
;                     for (int e = 0; e < 4; ++e) {
;                         const float p1 = fr >= 1 ? r1[e] : r1p[e], p2 = fr >= 2 ? r2[e] : r2p[e];
;                         const float gg = b4[e] + w0[e] * p2 + w1[e] * p1 + w2[e] * g[e];
;                         a[e] = gg * __builtin_amdgcn_rcpf(1.f + __expf(-gg)) * v[e];
;                     }
;                     r1p = r1; r2p = r2;
;                     const size_t row = (size_t)(u.pm * BM + ai * HALF + wr * 64 + m * 16 + fr);
;                     if (m == 0 && fr < 2) {
;                         *(f32x4*)(GF + (size_t)(slab * 2 + fr) * FF + cbase) = g; *(f32x4*)(VF + (size_t)(slab * 2 + fr) * FF + cbase) = v;
;                     } else {
;                         typedef unsigned u32x2v __attribute__((ext_vector_type(2)));
;                         u32x2v w; w.x = cvt_pk_bf16(a[0], a[1]); w.y = cvt_pk_bf16(a[2], a[3]);
;                         *(u32x2v*)(ACT + row * FF + cbase) = w;
.LBB0_41:
	v_lshl_add_u32 v160, s66, 8, v193
	v_ashrrev_i32_e32 v161, 31, v160
	v_mov_b32_e32 v148, v227
	v_bfe_u32 v205, v227, 4, 1
	v_mul_u32_u24_e32 v205, 24, v205
	v_lshl_add_u64 v[114:115], v[160:161], 3, s[56:57]
	global_load_dwordx2 v[146:147], v[114:115], off
	v_lshl_or_b32 v156, s64, 7, v198
	v_ashrrev_i32_e32 v157, 31, v156
	global_load_dwordx2 v[190:191], v[114:115], off offset:128
	global_load_dwordx2 v[188:189], v[114:115], off offset:256
	global_load_dwordx2 v[186:187], v[114:115], off offset:384
	global_load_dwordx2 v[176:177], v[114:115], off offset:1024
	global_load_dwordx2 v[174:175], v[114:115], off offset:1152
	global_load_dwordx2 v[172:173], v[114:115], off offset:1280
	global_load_dwordx2 v[170:171], v[114:115], off offset:1408
	v_lshlrev_b64 v[158:159], 2, v[156:157]
	v_lshl_add_u64 v[166:167], s[52:53], 0, v[158:159]
	v_lshl_add_u64 v[118:119], s[60:61], 0, v[158:159]
	v_lshl_add_u64 v[120:121], s[62:63], 0, v[158:159]
	v_lshl_add_u64 v[164:165], s[54:55], 0, v[158:159]
	global_load_dwordx4 v[114:117], v[166:167], off
	global_load_dwordx4 v[138:141], v[118:119], off
	global_load_dwordx4 v[130:133], v[120:121], off
	s_nop 0
	global_load_dwordx4 v[118:121], v[164:165], off
	s_waitcnt vmcnt(0)
	v_ffbh_u32_e32 v149, v147
	v_min_u32_e32 v149, 32, v149
	v_lshlrev_b64 v[146:147], v149, v[146:147]
	v_min_u32_e32 v146, 1, v146
	v_or_b32_e32 v146, v147, v146
	v_cvt_f32_u32_e32 v146, v146
	v_sub_u32_e32 v149, 32, v149
	v_and_b32_e32 v147, 48, v148
	v_or3_b32 v148, v147, v195, v236
	v_ldexp_f32 v146, v146, v149
	v_fmamk_f32 v146, v146, 0x31000000, v232
	v_rsq_f32_e32 v162, v146
	v_or3_b32 v146, v147, v196, v236
	v_lshlrev_b32_e32 v200, 2, v146
	v_lshlrev_b32_e32 v161, 2, v148
	v_pk_mul_f32 v[146:147], v[134:135], v[162:163] op_sel_hi:[1,0]
	v_pk_mul_f32 v[148:149], v[136:137], v[162:163] op_sel_hi:[1,0]
	s_nop 1
	v_mov_b32_dpp v163, v146 row_ror:2 row_mask:0xf bank_mask:0xf
	v_mov_b32_dpp v179, v146 row_ror:1 row_mask:0xf bank_mask:0xf
	v_mov_b32_dpp v181, v147 row_ror:1 row_mask:0xf bank_mask:0xf
	v_mov_b32_dpp v201, v147 row_ror:2 row_mask:0xf bank_mask:0xf
	v_mov_b32_dpp v183, v148 row_ror:1 row_mask:0xf bank_mask:0xf
	v_mov_b32_dpp v202, v148 row_ror:2 row_mask:0xf bank_mask:0xf
	v_mov_b32_dpp v185, v149 row_ror:1 row_mask:0xf bank_mask:0xf
	v_mov_b32_dpp v203, v149 row_ror:2 row_mask:0xf bank_mask:0xf
	s_waitcnt lgkmcnt(7)
	v_pk_mul_f32 v[136:137], v[144:145], v[162:163] op_sel_hi:[1,0]
	v_pk_mul_f32 v[134:135], v[142:143], v[162:163] op_sel_hi:[1,0]
	s_and_saveexec_b64 s[10:11], s[42:43]
	s_xor_b64 s[10:11], exec, s[10:11]
	s_movk_i32 s17, 0x2b00
	s_movk_i32 s84, 0x300
	s_mov_b32 s86, 0x24000
	s_mov_b32 s88, 0x48800000
	s_cbranch_execz .LBB0_43
	v_mov_b32_e32 v142, v149
	v_mov_b32_e32 v143, v141
	v_mov_b32_e32 v184, v133
	s_waitcnt lgkmcnt(1)
	v_pk_mul_f32 v[142:143], v[142:143], v[184:185]
	s_waitcnt lgkmcnt(0)
	v_fma_f32 v144, v117, v203, v121
	v_add_f32_e32 v143, v143, v144
	v_add_f32_e32 v142, v142, v143
	v_mul_f32_e32 v143, 0xbfb8aa3b, v142
	v_exp_f32_e32 v143, v143
	v_mov_b32_e32 v149, v140
	v_mov_b32_e32 v182, v132
	v_mov_b32_e32 v180, v131
	v_add_f32_e32 v143, 1.0, v143
	v_rcp_f32_e32 v143, v143
	v_mov_b32_e32 v178, v130
	v_mul_f32_e32 v142, v142, v143
	v_mul_f32_e32 v144, v137, v142
	v_pk_mul_f32 v[142:143], v[148:149], v[182:183]
	v_fma_f32 v137, v116, v202, v120
	v_add_f32_e32 v137, v143, v137
	v_add_f32_e32 v137, v142, v137
	v_mul_f32_e32 v142, 0xbfb8aa3b, v137
	v_exp_f32_e32 v142, v142
	v_fma_f32 v143, v115, v201, v119
	v_add_f32_e32 v142, 1.0, v142
	v_rcp_f32_e32 v142, v142
	s_nop 0
	v_mul_f32_e32 v137, v137, v142
	v_mul_f32_e32 v142, v136, v137
	v_mov_b32_e32 v136, v147
	v_mov_b32_e32 v137, v139
	v_pk_mul_f32 v[136:137], v[136:137], v[180:181]
	v_mov_b32_e32 v147, v138
	v_add_f32_e32 v137, v137, v143
	v_add_f32_e32 v136, v136, v137
	v_mul_f32_e32 v137, 0xbfb8aa3b, v136
	v_exp_f32_e32 v137, v137
	v_fma_f32 v143, v114, v163, v118
	v_add_f32_e32 v137, 1.0, v137
	v_rcp_f32_e32 v137, v137
	s_nop 0
	v_mul_f32_e32 v136, v136, v137
	v_mul_f32_e32 v135, v135, v136
	v_pk_mul_f32 v[136:137], v[146:147], v[178:179]
	s_nop 0
	v_add_f32_e32 v137, v137, v143
	v_add_f32_e32 v136, v136, v137
	v_mul_f32_e32 v137, 0xbfb8aa3b, v136
	v_exp_f32_e32 v137, v137
	s_nop 0
	v_add_f32_e32 v137, 1.0, v137
	v_rcp_f32_e32 v137, v137
	s_nop 0
	v_mul_f32_e32 v136, v136, v137
	v_mul_f32_e32 v134, v134, v136
	v_mov_b64_e32 v[136:137], s[48:49]
	v_mad_i64_i32 v[136:137], s[12:13], v160, s17, v[136:137]
	v_cvt_pk_bf16_f32 v134, v134, v135
	v_cvt_pk_bf16_f32 v135, v142, v144
	v_lshl_add_u64 v[136:137], v[156:157], 1, v[136:137]
	v_mov_b32_e32 v220, v134
	v_mov_b32_e32 v221, v135

; __device__ __forceinline__ unsigned cvt_pk_bf16(float lo, float hi) { unsigned r; asm volatile("v_cvt_pk_bf16_f32 %0, %1, %2" : "=v"(r) : "v"(lo), "v"(hi)); return r; }
;     __device__ __forceinline__ void operator()(const f32x4 (&acc)[2][2][4][2], const Unit& u, int wr, int wc, int fr, int fq) const {
;     ...
;                     const f32x4 g = acc[ai][1][m][n] * rs[ai][m], v = acc[ai][0][m][n] * rs[ai][m];
;                     f32x4 r1, r2, a;
; #pragma unroll
;                     for (int e = 0; e < 4; ++e) { r1[e] = __shfl(g[e], src1); r2[e] = __shfl(g[e], src2); }
; #pragma unroll
;                     for (int e = 0; e < 4; ++e) {
;                         const float p1 = fr >= 1 ? r1[e] : r1p[e], p2 = fr >= 2 ? r2[e] : r2p[e];
;                         const float gg = b4[e] + w0[e] * p2 + w1[e] * p1 + w2[e] * g[e];
;                         a[e] = gg * __builtin_amdgcn_rcpf(1.f + __expf(-gg)) * v[e];
;                     }
;                     r1p = r1; r2p = r2;
;                     const size_t row = (size_t)(u.pm * BM + ai * HALF + wr * 64 + m * 16 + fr);
;                     if (m == 0 && fr < 2) {
;                         *(f32x4*)(GF + (size_t)(slab * 2 + fr) * FF + cbase) = g; *(f32x4*)(VF + (size_t)(slab * 2 + fr) * FF + cbase) = v;
;                     } else {
;                         typedef unsigned u32x2v __attribute__((ext_vector_type(2)));
;                         u32x2v w; w.x = cvt_pk_bf16(a[0], a[1]); w.y = cvt_pk_bf16(a[2], a[3]);
;                         *(u32x2v*)(ACT + row * FF + cbase) = w;
.LBB0_45:
	s_or_b64 exec, exec, s[10:11]
	s_nop 0
	v_ffbh_u32_e32 v134, v191
	v_min_u32_e32 v136, 32, v134
	v_lshlrev_b64 v[134:135], v136, v[190:191]
	v_min_u32_e32 v134, 1, v134
	v_or_b32_e32 v134, v135, v134
	v_cvt_f32_u32_e32 v134, v134
	v_ffbh_u32_e32 v135, v189
	v_sub_u32_e32 v136, 32, v136
	v_min_u32_e32 v143, 32, v135
	v_ldexp_f32 v134, v134, v136
	v_fmamk_f32 v136, v134, 0x31000000, v232
	v_lshlrev_b64 v[134:135], v143, v[188:189]
	v_min_u32_e32 v134, 1, v134
	v_or_b32_e32 v134, v135, v134
	v_cvt_f32_u32_e32 v134, v134
	v_sub_u32_e32 v135, 32, v143
	v_rsq_f32_e32 v142, v136
	v_mov_b32_e32 v149, v141
	v_ldexp_f32 v134, v134, v135
	v_fmamk_f32 v136, v134, 0x31000000, v232
	v_ffbh_u32_e32 v134, v187
	v_min_u32_e32 v143, 32, v134
	v_lshlrev_b64 v[134:135], v143, v[186:187]
	v_min_u32_e32 v134, 1, v134
	v_or_b32_e32 v134, v135, v134
	v_cvt_f32_u32_e32 v134, v134
	v_sub_u32_e32 v143, 32, v143
	s_movk_i32 s10, 0x5600
	v_rsq_f32_e32 v136, v136
	v_ldexp_f32 v134, v134, v143
	v_add_u32_e32 v143, s12, v197
	v_pk_mul_f32 v[128:129], v[128:129], v[142:143] op_sel_hi:[1,0]
	s_nop 1
	v_mov_b32_dpp v186, v129 row_ror:1 row_mask:0xf bank_mask:0xf
	v_mov_b32_dpp v191, v129 row_ror:2 row_mask:0xf bank_mask:0xf
	v_mov_b32_e32 v148, v129
	v_pk_mul_f32 v[126:127], v[126:127], v[142:143] op_sel_hi:[1,0]
	v_mad_i64_i32 v[146:147], s[10:11], v143, s10, 0
	s_waitcnt lgkmcnt(1)
	v_cndmask_b32_e64 v185, v186, v185, s[40:41]
	s_waitcnt lgkmcnt(0)
	v_cndmask_b32_e64 v129, v203, v191, s[42:43]
	v_pk_mul_f32 v[148:149], v[148:149], v[184:185]
	v_fma_f32 v129, v117, v129, v121
	v_add_f32_e32 v129, v149, v129
	v_add_f32_e32 v148, v148, v129
	v_mul_f32_e32 v129, 0xbfb8aa3b, v148
	v_exp_f32_e32 v129, v129
	v_mov_b32_dpp v149, v128 row_ror:1 row_mask:0xf bank_mask:0xf
	v_mov_b32_dpp v203, v128 row_ror:2 row_mask:0xf bank_mask:0xf
	v_mov_b32_dpp v143, v126 row_ror:1 row_mask:0xf bank_mask:0xf
	v_add_f32_e32 v129, 1.0, v129
	v_rcp_f32_e32 v185, v129
	s_waitcnt lgkmcnt(2)
	v_cndmask_b32_e64 v183, v149, v183, s[40:41]
	v_mov_b32_e32 v129, v140
	v_pk_mul_f32 v[128:129], v[128:129], v[182:183]
	s_waitcnt lgkmcnt(1)
	v_cndmask_b32_e64 v183, v202, v203, s[42:43]
	v_fma_f32 v183, v116, v183, v120
	v_add_f32_e32 v129, v129, v183
	v_add_f32_e32 v183, v128, v129
	v_mul_f32_e32 v128, 0xbfb8aa3b, v183
	v_mov_b32_dpp v189, v127 row_ror:1 row_mask:0xf bank_mask:0xf
	v_mov_b32_dpp v190, v127 row_ror:2 row_mask:0xf bank_mask:0xf
	v_exp_f32_e32 v128, v128
	s_waitcnt lgkmcnt(2)
	v_pk_mul_f32 v[124:125], v[124:125], v[142:143] op_sel_hi:[1,0]
	v_mul_f32_e32 v129, v148, v185
	v_mov_b32_dpp v187, v126 row_ror:2 row_mask:0xf bank_mask:0xf
	v_add_f32_e32 v128, 1.0, v128
	v_mul_f32_e32 v125, v125, v129
	v_rcp_f32_e32 v148, v128
	s_waitcnt lgkmcnt(2)
	v_cndmask_b32_e64 v181, v189, v181, s[40:41]
	v_mov_b32_e32 v128, v127
	v_mov_b32_e32 v129, v139
	s_waitcnt lgkmcnt(1)
	v_cndmask_b32_e64 v127, v201, v190, s[42:43]
	v_pk_mul_f32 v[128:129], v[128:129], v[180:181]
	v_fma_f32 v127, v115, v127, v119
	v_add_f32_e32 v127, v129, v127
	v_add_f32_e32 v128, v128, v127
	v_mul_f32_e32 v127, 0xbfb8aa3b, v128
	v_exp_f32_e32 v129, v127
	v_cndmask_b32_e64 v179, v143, v179, s[40:41]
	v_mov_b32_e32 v127, v138
	s_waitcnt lgkmcnt(0)
	v_cndmask_b32_e64 v163, v163, v187, s[42:43]
	v_pk_mul_f32 v[126:127], v[126:127], v[178:179]
	v_fma_f32 v163, v114, v163, v118
	v_add_f32_e32 v127, v127, v163
	v_add_f32_e32 v126, v126, v127
	v_mul_f32_e32 v127, 0xbfb8aa3b, v126
	v_exp_f32_e32 v127, v127
	v_add_f32_e32 v129, 1.0, v129
	v_rcp_f32_e32 v129, v129
	v_or_b32_e32 v137, 16, v160
	v_add_f32_e32 v127, 1.0, v127
	v_rcp_f32_e32 v127, v127
	v_mul_f32_e32 v148, v183, v148
	v_pk_mul_f32 v[112:113], v[112:113], v[136:137] op_sel_hi:[1,0]
	v_mul_f32_e32 v124, v124, v148
	s_nop 1
	v_mov_b32_dpp v148, v113 row_ror:1 row_mask:0xf bank_mask:0xf
	v_mov_b32_dpp v204, v113 row_ror:2 row_mask:0xf bank_mask:0xf
	v_pk_mul_f32 v[122:123], v[122:123], v[142:143] op_sel_hi:[1,0]
	v_mul_f32_e32 v128, v128, v129
	v_mul_f32_e32 v126, v126, v127
	v_mul_f32_e32 v123, v123, v128
	v_mul_f32_e32 v122, v122, v126
	v_mov_b64_e32 v[128:129], s[48:49]
	v_cvt_pk_bf16_f32 v126, v122, v123
	v_cvt_pk_bf16_f32 v127, v124, v125
	v_mad_i64_i32 v[122:123], s[10:11], v137, s17, v[128:129]
	v_lshlrev_b64 v[124:125], 1, v[156:157]
	v_lshl_add_u64 v[122:123], v[122:123], 0, v[124:125]
	v_mov_b32_e32 v206, v126
	v_mov_b32_e32 v207, v127
	s_waitcnt lgkmcnt(1)
	v_cndmask_b32_e64 v185, v148, v186, s[40:41]
	v_mov_b32_e32 v126, v113
	v_mov_b32_e32 v127, v141
	s_waitcnt lgkmcnt(0)
	v_cndmask_b32_e64 v113, v191, v204, s[42:43]
	v_pk_mul_f32 v[126:127], v[126:127], v[184:185]
	v_fma_f32 v113, v117, v113, v121
	v_add_f32_e32 v113, v127, v113
	v_add_f32_e32 v126, v126, v113
	v_mul_f32_e32 v113, 0xbfb8aa3b, v126
	v_exp_f32_e32 v113, v113
	v_mov_b32_dpp v127, v112 row_ror:1 row_mask:0xf bank_mask:0xf
	v_mov_b32_dpp v186, v112 row_ror:2 row_mask:0xf bank_mask:0xf
	v_pk_mul_f32 v[110:111], v[110:111], v[136:137] op_sel_hi:[1,0]
	v_add_f32_e32 v113, 1.0, v113
	v_rcp_f32_e32 v179, v113
	s_waitcnt lgkmcnt(1)
	v_cndmask_b32_e64 v183, v127, v149, s[40:41]
	v_mov_b32_e32 v113, v140
	s_waitcnt lgkmcnt(0)
	v_cndmask_b32_e64 v149, v203, v186, s[42:43]
	v_pk_mul_f32 v[112:113], v[112:113], v[182:183]
	v_fma_f32 v149, v116, v149, v120
	v_add_f32_e32 v113, v113, v149
	v_add_f32_e32 v149, v112, v113
	v_mov_b32_dpp v137, v110 row_ror:1 row_mask:0xf bank_mask:0xf
	v_mul_f32_e32 v112, 0xbfb8aa3b, v149
	v_mov_b32_dpp v201, v111 row_ror:1 row_mask:0xf bank_mask:0xf
	v_mov_b32_dpp v202, v111 row_ror:2 row_mask:0xf bank_mask:0xf
	v_exp_f32_e32 v112, v112
	s_waitcnt lgkmcnt(2)
; __device__ __forceinline__ unsigned cvt_pk_bf16(float lo, float hi) { unsigned r; asm volatile("v_cvt_pk_bf16_f32 %0, %1, %2" : "=v"(r) : "v"(lo), "v"(hi)); return r; }
;     __device__ __forceinline__ void operator()(const f32x4 (&acc)[2][2][4][2], const Unit& u, int wr, int wc, int fr, int fq) const {
;     ...
;                     const f32x4 g = acc[ai][1][m][n] * rs[ai][m], v = acc[ai][0][m][n] * rs[ai][m];
;                     f32x4 r1, r2, a;
; #pragma unroll
;                     for (int e = 0; e < 4; ++e) { r1[e] = __shfl(g[e], src1); r2[e] = __shfl(g[e], src2); }
; #pragma unroll
;                     for (int e = 0; e < 4; ++e) {
;                         const float p1 = fr >= 1 ? r1[e] : r1p[e], p2 = fr >= 2 ? r2[e] : r2p[e];
;                         const float gg = b4[e] + w0[e] * p2 + w1[e] * p1 + w2[e] * g[e];
;                         a[e] = gg * __builtin_amdgcn_rcpf(1.f + __expf(-gg)) * v[e];
;                     }
;                     r1p = r1; r2p = r2;
;                     const size_t row = (size_t)(u.pm * BM + ai * HALF + wr * 64 + m * 16 + fr);
;                     if (m == 0 && fr < 2) {
;                         *(f32x4*)(GF + (size_t)(slab * 2 + fr) * FF + cbase) = g; *(f32x4*)(VF + (size_t)(slab * 2 + fr) * FF + cbase) = v;
;                     } else {
;                         typedef unsigned u32x2v __attribute__((ext_vector_type(2)));
;                         u32x2v w; w.x = cvt_pk_bf16(a[0], a[1]); w.y = cvt_pk_bf16(a[2], a[3]);
;                         *(u32x2v*)(ACT + row * FF + cbase) = w;
;                     }
;                     if (m == 3 && fr >= 14) *(f32x4*)(GL + (size_t)(slab * 2 + fr - 14) * FF + cbase) = g;
	v_pk_mul_f32 v[108:109], v[108:109], v[136:137] op_sel_hi:[1,0]
	v_mul_f32_e32 v113, v126, v179
	v_mov_b32_dpp v163, v110 row_ror:2 row_mask:0xf bank_mask:0xf
	v_add_f32_e32 v112, 1.0, v112
	v_mul_f32_e32 v109, v109, v113
	v_rcp_f32_e32 v126, v112
	s_waitcnt lgkmcnt(2)
	v_cndmask_b32_e64 v181, v201, v189, s[40:41]
	v_mov_b32_e32 v112, v111
	v_mov_b32_e32 v113, v139
	s_waitcnt lgkmcnt(1)
	v_cndmask_b32_e64 v111, v190, v202, s[42:43]
	v_pk_mul_f32 v[112:113], v[112:113], v[180:181]
	v_fma_f32 v111, v115, v111, v119
	v_add_f32_e32 v111, v113, v111
	v_add_f32_e32 v112, v112, v111
	v_mul_f32_e32 v111, 0xbfb8aa3b, v112
	v_exp_f32_e32 v113, v111
	v_cndmask_b32_e64 v179, v137, v143, s[40:41]
	v_mov_b32_e32 v111, v138
	s_waitcnt lgkmcnt(0)
	v_cndmask_b32_e64 v143, v187, v163, s[42:43]
	v_pk_mul_f32 v[110:111], v[110:111], v[178:179]
	v_fma_f32 v143, v114, v143, v118
	v_add_f32_e32 v111, v111, v143
	v_add_f32_e32 v110, v110, v111
	v_mul_f32_e32 v111, 0xbfb8aa3b, v110
	v_exp_f32_e32 v111, v111
	v_add_f32_e32 v113, 1.0, v113
	v_rcp_f32_e32 v113, v113
	v_fmamk_f32 v134, v134, 0x31000000, v232
	v_add_f32_e32 v111, 1.0, v111
	v_rcp_f32_e32 v111, v111
	v_rsq_f32_e32 v134, v134
	v_pk_mul_f32 v[106:107], v[106:107], v[136:137] op_sel_hi:[1,0]
	v_mul_f32_e32 v126, v149, v126
	v_mul_f32_e32 v112, v112, v113
	v_mul_f32_e32 v110, v110, v111
	v_or_b32_e32 v188, 32, v160
	v_mul_f32_e32 v108, v108, v126
	v_mul_f32_e32 v107, v107, v112
	v_mul_f32_e32 v106, v106, v110
	v_or_b32_e32 v135, 48, v160
	v_cvt_pk_bf16_f32 v106, v106, v107
	v_cvt_pk_bf16_f32 v107, v108, v109
	v_mad_i64_i32 v[108:109], s[10:11], v188, s17, v[128:129]
	v_lshl_add_u64 v[108:109], v[108:109], 0, v[124:125]
	v_pk_mul_f32 v[104:105], v[104:105], v[134:135] op_sel_hi:[1,0]
	v_mov_b32_e32 v208, v106
	v_mov_b32_e32 v209, v107
	v_mov_b32_dpp v106, v105 row_ror:1 row_mask:0xf bank_mask:0xf
	v_mov_b32_dpp v126, v105 row_ror:2 row_mask:0xf bank_mask:0xf
	v_mov_b32_e32 v107, v141
	v_mov_b32_dpp v143, v104 row_ror:2 row_mask:0xf bank_mask:0xf
	v_pk_mul_f32 v[102:103], v[102:103], v[134:135] op_sel_hi:[1,0]
	s_waitcnt lgkmcnt(2)
	v_cndmask_b32_e64 v185, v106, v148, s[40:41]
	v_mov_b32_e32 v106, v105
	s_waitcnt lgkmcnt(1)
	v_cndmask_b32_e64 v126, v204, v126, s[42:43]
	v_pk_mul_f32 v[106:107], v[106:107], v[184:185]
	v_fma_f32 v126, v117, v126, v121
	v_add_f32_e32 v107, v107, v126
	v_add_f32_e32 v126, v106, v107
	v_mul_f32_e32 v106, 0xbfb8aa3b, v126
	v_exp_f32_e32 v106, v106
	v_mov_b32_dpp v107, v104 row_ror:1 row_mask:0xf bank_mask:0xf
	v_mov_b32_dpp v112, v103 row_ror:1 row_mask:0xf bank_mask:0xf
	v_mov_b32_dpp v113, v103 row_ror:2 row_mask:0xf bank_mask:0xf
	v_add_f32_e32 v106, 1.0, v106
	v_rcp_f32_e32 v148, v106
	s_waitcnt lgkmcnt(2)
	v_cndmask_b32_e64 v183, v107, v127, s[40:41]
	v_mov_b32_e32 v106, v104
	v_mov_b32_e32 v107, v140
	v_cndmask_b32_e64 v127, v186, v143, s[42:43]
	v_pk_mul_f32 v[106:107], v[106:107], v[182:183]
	v_fma_f32 v127, v116, v127, v120
	v_add_f32_e32 v107, v107, v127
	v_add_f32_e32 v127, v106, v107
	v_mul_f32_e32 v106, 0xbfb8aa3b, v127
	v_exp_f32_e32 v106, v106
	v_pk_mul_f32 v[100:101], v[100:101], v[134:135] op_sel_hi:[1,0]
	v_mul_f32_e32 v107, v126, v148
	v_mov_b32_dpp v110, v102 row_ror:1 row_mask:0xf bank_mask:0xf
	v_add_f32_e32 v106, 1.0, v106
	v_mov_b32_dpp v111, v102 row_ror:2 row_mask:0xf bank_mask:0xf
	v_mul_f32_e32 v101, v101, v107
	v_rcp_f32_e32 v126, v106
	s_waitcnt lgkmcnt(3)
	v_cndmask_b32_e64 v181, v112, v201, s[40:41]
	v_mov_b32_e32 v106, v103
	v_mov_b32_e32 v107, v139
	s_waitcnt lgkmcnt(2)
	v_cndmask_b32_e64 v112, v202, v113, s[42:43]
	v_pk_mul_f32 v[106:107], v[106:107], v[180:181]
	v_fma_f32 v112, v115, v112, v119
	v_add_f32_e32 v107, v107, v112
	v_add_f32_e32 v112, v106, v107
	v_mul_f32_e32 v106, 0xbfb8aa3b, v112
	v_exp_f32_e32 v113, v106
	s_waitcnt lgkmcnt(1)
	v_cndmask_b32_e64 v179, v110, v137, s[40:41]
	v_mov_b32_e32 v106, v102
	v_mov_b32_e32 v107, v138
	s_waitcnt lgkmcnt(0)
	v_cndmask_b32_e64 v110, v163, v111, s[42:43]
	v_pk_mul_f32 v[106:107], v[106:107], v[178:179]
	v_fma_f32 v110, v114, v110, v118
	v_add_f32_e32 v107, v107, v110
	v_add_f32_e32 v106, v106, v107
	v_mul_f32_e32 v107, 0xbfb8aa3b, v106
	v_exp_f32_e32 v107, v107
	v_add_f32_e32 v111, 1.0, v113
	v_rcp_f32_e32 v111, v111
	v_mul_f32_e32 v110, v127, v126
	v_add_f32_e32 v107, 1.0, v107
	v_rcp_f32_e32 v107, v107
	v_pk_mul_f32 v[98:99], v[98:99], v[134:135] op_sel_hi:[1,0]
	v_mul_f32_e32 v100, v100, v110
	v_mul_f32_e32 v110, v112, v111
	v_mul_f32_e32 v106, v106, v107
	v_mul_f32_e32 v99, v99, v110
	v_mul_f32_e32 v98, v98, v106
	v_cvt_pk_bf16_f32 v98, v98, v99
	v_cvt_pk_bf16_f32 v99, v100, v101
	v_mad_i64_i32 v[100:101], s[10:11], v135, s17, v[128:129]
	v_readlane_b32 s10, v254, 44
	v_lshl_add_u64 v[110:111], v[100:101], 0, v[124:125]
	v_readlane_b32 s11, v254, 45
	v_mov_b32_e32 v210, v98
	v_mov_b32_e32 v211, v99
	s_nop 0
	v_lshl_add_u64 v[98:99], s[10:11], 0, v[146:147]
	v_lshl_add_u64 v[106:107], v[156:157], 2, v[98:99]
	s_and_saveexec_b64 s[10:11], s[44:45]
	v_readlane_b32 s85, v254, 57
	v_readlane_b32 s93, v254, 58
	s_cbranch_execz .LBB0_47
	global_store_dwordx4 v[106:107], v[102:105], off
; __device__ __forceinline__ unsigned cvt_pk_bf16(float lo, float hi) { unsigned r; asm volatile("v_cvt_pk_bf16_f32 %0, %1, %2" : "=v"(r) : "v"(lo), "v"(hi)); return r; }
;     __device__ __forceinline__ void operator()(const f32x4 (&acc)[2][2][4][2], const Unit& u, int wr, int wc, int fr, int fq) const {
;     ...
;                 const int slab = u.pm * 4 + 2 * ai + wr;
;                 f32x4 r1p = (f32x4){0.f, 0.f, 0.f, 0.f}, r2p = (f32x4){0.f, 0.f, 0.f, 0.f};
; #pragma unroll
;                 for (int m = 0; m < 4; ++m) {
;                     const f32x4 g = acc[ai][1][m][n] * rs[ai][m], v = acc[ai][0][m][n] * rs[ai][m];
;                     f32x4 r1, r2, a;
; #pragma unroll
;                     for (int e = 0; e < 4; ++e) { r1[e] = __shfl(g[e], src1); r2[e] = __shfl(g[e], src2); }
; #pragma unroll
;                     for (int e = 0; e < 4; ++e) {
;                         const float p1 = fr >= 1 ? r1[e] : r1p[e], p2 = fr >= 2 ? r2[e] : r2p[e];
;                         const float gg = b4[e] + w0[e] * p2 + w1[e] * p1 + w2[e] * g[e];
;                         a[e] = gg * __builtin_amdgcn_rcpf(1.f + __expf(-gg)) * v[e];
;                     }
;                     r1p = r1; r2p = r2;
;                     const size_t row = (size_t)(u.pm * BM + ai * HALF + wr * 64 + m * 16 + fr);
;                     if (m == 0 && fr < 2) {
;                         *(f32x4*)(GF + (size_t)(slab * 2 + fr) * FF + cbase) = g; *(f32x4*)(VF + (size_t)(slab * 2 + fr) * FF + cbase) = v;
;                     } else {
;                         typedef unsigned u32x2v __attribute__((ext_vector_type(2)));
;                         u32x2v w; w.x = cvt_pk_bf16(a[0], a[1]); w.y = cvt_pk_bf16(a[2], a[3]);
;                         *(u32x2v*)(ACT + row * FF + cbase) = w;
.LBB0_47:
	s_or_b64 exec, exec, s[10:11]
	v_ffbh_u32_e32 v98, v177
	v_min_u32_e32 v100, 32, v98
	v_lshlrev_b64 v[98:99], v100, v[176:177]
	v_min_u32_e32 v98, 1, v98
	v_or_b32_e32 v98, v99, v98
	v_cvt_f32_u32_e32 v98, v98
	v_sub_u32_e32 v99, 32, v100
	v_add_u32_e32 v180, 0x80, v160
	v_mov_b32_e32 v146, v130
	v_ldexp_f32 v98, v98, v99
	v_fmamk_f32 v98, v98, 0x31000000, v232
	v_rsq_f32_e32 v102, v98
	v_mov_b32_e32 v147, v138
	v_mov_b32_e32 v128, v131
	v_mov_b32_e32 v129, v139
	v_pk_mul_f32 v[98:99], v[90:91], v[102:103] op_sel_hi:[1,0]
	v_pk_mul_f32 v[100:101], v[92:93], v[102:103] op_sel_hi:[1,0]
	s_nop 1
	v_mov_b32_dpp v103, v98 row_ror:2 row_mask:0xf bank_mask:0xf
	v_mov_b32_dpp v135, v98 row_ror:1 row_mask:0xf bank_mask:0xf
	v_mov_b32_dpp v177, v99 row_ror:1 row_mask:0xf bank_mask:0xf
	v_mov_b32_dpp v137, v99 row_ror:2 row_mask:0xf bank_mask:0xf
	v_mov_b32_dpp v163, v100 row_ror:1 row_mask:0xf bank_mask:0xf
	v_mov_b32_dpp v143, v100 row_ror:2 row_mask:0xf bank_mask:0xf
	v_mov_b32_dpp v179, v101 row_ror:1 row_mask:0xf bank_mask:0xf
	v_mov_b32_dpp v181, v101 row_ror:2 row_mask:0xf bank_mask:0xf
	s_waitcnt lgkmcnt(7)
	v_pk_mul_f32 v[92:93], v[96:97], v[102:103] op_sel_hi:[1,0]
	v_pk_mul_f32 v[90:91], v[94:95], v[102:103] op_sel_hi:[1,0]
	v_mov_b32_e32 v148, v132
	v_mov_b32_e32 v149, v140
	v_mov_b32_e32 v126, v133
	v_mov_b32_e32 v127, v141
	s_and_saveexec_b64 s[10:11], s[42:43]
	s_xor_b64 s[10:11], exec, s[10:11]
	s_cbranch_execz .LBB0_49
	v_mov_b32_e32 v126, v133
	v_mov_b32_e32 v127, v141
	v_mov_b32_e32 v178, v101
	s_waitcnt lgkmcnt(1)
	v_pk_mul_f32 v[94:95], v[126:127], v[178:179]
	s_waitcnt lgkmcnt(0)
	v_fma_f32 v96, v117, v181, v121
	v_add_f32_e32 v95, v95, v96
	v_add_f32_e32 v94, v94, v95
	v_mul_f32_e32 v95, 0xbfb8aa3b, v94
	v_exp_f32_e32 v95, v95
	v_mov_b32_e32 v133, v140
	v_mov_b32_e32 v101, v163
	v_mov_b32_e32 v128, v131
	v_add_f32_e32 v95, 1.0, v95
	v_rcp_f32_e32 v95, v95
	v_mov_b32_e32 v129, v139
	v_mov_b32_e32 v176, v99
	v_mov_b32_e32 v131, v138
	v_mul_f32_e32 v94, v94, v95
	v_mul_f32_e32 v96, v93, v94
	v_pk_mul_f32 v[94:95], v[132:133], v[100:101]
	v_fma_f32 v93, v116, v143, v120
	v_add_f32_e32 v93, v95, v93
	v_add_f32_e32 v93, v94, v93
	v_mul_f32_e32 v94, 0xbfb8aa3b, v93
	v_exp_f32_e32 v94, v94
	v_fma_f32 v95, v115, v137, v119
	v_mov_b32_e32 v99, v135
	v_mov_b64_e32 v[148:149], v[132:133]
	v_add_f32_e32 v94, 1.0, v94
	v_rcp_f32_e32 v94, v94
	v_mov_b64_e32 v[146:147], v[130:131]
	v_mul_f32_e32 v93, v93, v94
	v_mul_f32_e32 v94, v92, v93
	v_pk_mul_f32 v[92:93], v[128:129], v[176:177]
	s_nop 0
	v_add_f32_e32 v93, v93, v95
	v_add_f32_e32 v92, v92, v93
	v_mul_f32_e32 v93, 0xbfb8aa3b, v92
	v_exp_f32_e32 v93, v93
	v_fma_f32 v95, v114, v103, v118
	v_add_f32_e32 v93, 1.0, v93
	v_rcp_f32_e32 v93, v93
	s_nop 0
	v_mul_f32_e32 v92, v92, v93
	v_mul_f32_e32 v91, v91, v92
	v_pk_mul_f32 v[92:93], v[130:131], v[98:99]
	s_nop 0
	v_add_f32_e32 v93, v93, v95
	v_add_f32_e32 v92, v92, v93
	v_mul_f32_e32 v93, 0xbfb8aa3b, v92
	v_exp_f32_e32 v93, v93
	s_nop 0
	v_add_f32_e32 v93, 1.0, v93
	v_rcp_f32_e32 v93, v93
	s_nop 0
	v_mul_f32_e32 v92, v92, v93
	v_mul_f32_e32 v90, v90, v92
	v_mov_b64_e32 v[92:93], s[48:49]
	v_mad_i64_i32 v[92:93], s[68:69], v180, s17, v[92:93]
	v_cvt_pk_bf16_f32 v90, v90, v91
	v_cvt_pk_bf16_f32 v91, v94, v96
	v_lshl_add_u64 v[92:93], v[156:157], 1, v[92:93]
	v_mov_b32_e32 v212, v90
	v_mov_b32_e32 v213, v91

; __device__ __forceinline__ unsigned cvt_pk_bf16(float lo, float hi) { unsigned r; asm volatile("v_cvt_pk_bf16_f32 %0, %1, %2" : "=v"(r) : "v"(lo), "v"(hi)); return r; }
;     __device__ __forceinline__ void operator()(const f32x4 (&acc)[2][2][4][2], const Unit& u, int wr, int wc, int fr, int fq) const {
;     ...
;                     const f32x4 g = acc[ai][1][m][n] * rs[ai][m], v = acc[ai][0][m][n] * rs[ai][m];
;                     f32x4 r1, r2, a;
; #pragma unroll
;                     for (int e = 0; e < 4; ++e) { r1[e] = __shfl(g[e], src1); r2[e] = __shfl(g[e], src2); }
; #pragma unroll
;                     for (int e = 0; e < 4; ++e) {
;                         const float p1 = fr >= 1 ? r1[e] : r1p[e], p2 = fr >= 2 ? r2[e] : r2p[e];
;                         const float gg = b4[e] + w0[e] * p2 + w1[e] * p1 + w2[e] * g[e];
;                         a[e] = gg * __builtin_amdgcn_rcpf(1.f + __expf(-gg)) * v[e];
;                     }
;                     r1p = r1; r2p = r2;
;                     const size_t row = (size_t)(u.pm * BM + ai * HALF + wr * 64 + m * 16 + fr);
;                     if (m == 0 && fr < 2) {
;                         *(f32x4*)(GF + (size_t)(slab * 2 + fr) * FF + cbase) = g; *(f32x4*)(VF + (size_t)(slab * 2 + fr) * FF + cbase) = v;
;                     } else {
;                         typedef unsigned u32x2v __attribute__((ext_vector_type(2)));
;                         u32x2v w; w.x = cvt_pk_bf16(a[0], a[1]); w.y = cvt_pk_bf16(a[2], a[3]);
;                         *(u32x2v*)(ACT + row * FF + cbase) = w;
.LBB0_51:
	s_or_b64 exec, exec, s[10:11]
	s_nop 0
	v_ffbh_u32_e32 v90, v175
	v_min_u32_e32 v93, 32, v90
	v_lshlrev_b64 v[90:91], v93, v[174:175]
	v_min_u32_e32 v90, 1, v90
	v_or_b32_e32 v90, v91, v90
	v_cvt_f32_u32_e32 v90, v90
	v_sub_u32_e32 v91, 32, v93
	v_add_u32_e32 v92, s12, v197
	s_movk_i32 s10, 0x5600
	v_ldexp_f32 v90, v90, v91
	v_mad_i64_i32 v[100:101], s[10:11], v92, s10, 0
	v_fmamk_f32 v92, v90, 0x31000000, v232
	v_rsq_f32_e32 v94, v92
	v_add_u32_e32 v95, 0x90, v160
	v_ffbh_u32_e32 v90, v173
	v_min_u32_e32 v93, 32, v90
	v_pk_mul_f32 v[88:89], v[88:89], v[94:95] op_sel_hi:[1,0]
	s_nop 1
	v_mov_b32_dpp v131, v89 row_ror:1 row_mask:0xf bank_mask:0xf
	v_mov_b32_dpp v138, v89 row_ror:2 row_mask:0xf bank_mask:0xf
	v_mov_b32_e32 v96, v89
	v_lshlrev_b64 v[90:91], v93, v[172:173]
	v_min_u32_e32 v90, 1, v90
	s_waitcnt lgkmcnt(1)
	v_cndmask_b32_e64 v97, v131, v179, s[40:41]
	s_waitcnt lgkmcnt(0)
	v_cndmask_b32_e64 v89, v181, v138, s[42:43]
	v_pk_mul_f32 v[96:97], v[126:127], v[96:97]
	v_fma_f32 v89, v117, v89, v121
	v_add_f32_e32 v89, v97, v89
	v_add_f32_e32 v96, v96, v89
	v_mul_f32_e32 v89, 0xbfb8aa3b, v96
	v_or_b32_e32 v90, v91, v90
	v_exp_f32_e32 v89, v89
	v_mov_b32_dpp v97, v88 row_ror:1 row_mask:0xf bank_mask:0xf
	v_mov_b32_dpp v140, v88 row_ror:2 row_mask:0xf bank_mask:0xf
	v_cvt_f32_u32_e32 v90, v90
	v_sub_u32_e32 v91, 32, v93
	v_add_f32_e32 v89, 1.0, v89
	v_rcp_f32_e32 v98, v89
	v_ldexp_f32 v90, v90, v91
	s_waitcnt lgkmcnt(1)
	v_cndmask_b32_e64 v89, v97, v163, s[40:41]
	s_waitcnt lgkmcnt(0)
	v_cndmask_b32_e64 v99, v143, v140, s[42:43]
	v_fmamk_f32 v92, v90, 0x31000000, v232
	v_ffbh_u32_e32 v90, v171
	v_pk_mul_f32 v[88:89], v[148:149], v[88:89]
	v_fma_f32 v99, v116, v99, v120
	v_min_u32_e32 v93, 32, v90
	v_add_f32_e32 v89, v89, v99
	v_lshlrev_b64 v[90:91], v93, v[170:171]
	v_add_f32_e32 v99, v88, v89
	v_min_u32_e32 v90, 1, v90
	v_pk_mul_f32 v[86:87], v[86:87], v[94:95] op_sel_hi:[1,0]
	v_mul_f32_e32 v88, 0xbfb8aa3b, v99
	v_or_b32_e32 v90, v91, v90
	v_mov_b32_dpp v133, v87 row_ror:1 row_mask:0xf bank_mask:0xf
	v_mov_b32_dpp v139, v87 row_ror:2 row_mask:0xf bank_mask:0xf
	v_exp_f32_e32 v88, v88
	v_cvt_f32_u32_e32 v90, v90
	v_sub_u32_e32 v93, 32, v93
	v_pk_mul_f32 v[84:85], v[84:85], v[94:95] op_sel_hi:[1,0]
	v_mul_f32_e32 v89, v96, v98
	v_add_f32_e32 v88, 1.0, v88
	v_ldexp_f32 v90, v90, v93
	v_mov_b32_dpp v93, v86 row_ror:1 row_mask:0xf bank_mask:0xf
	v_mov_b32_dpp v132, v86 row_ror:2 row_mask:0xf bank_mask:0xf
	v_mul_f32_e32 v85, v85, v89
	v_rcp_f32_e32 v96, v88
	s_waitcnt lgkmcnt(3)
	v_cndmask_b32_e64 v89, v133, v177, s[40:41]
	v_mov_b32_e32 v88, v87
	s_waitcnt lgkmcnt(2)
	v_cndmask_b32_e64 v87, v137, v139, s[42:43]
	v_pk_mul_f32 v[88:89], v[128:129], v[88:89]
	v_fma_f32 v87, v115, v87, v119
	v_add_f32_e32 v87, v89, v87
	v_add_f32_e32 v88, v88, v87
	v_mul_f32_e32 v87, 0xbfb8aa3b, v88
	v_exp_f32_e32 v89, v87
	s_waitcnt lgkmcnt(1)
	v_cndmask_b32_e64 v87, v93, v135, s[40:41]
	s_waitcnt lgkmcnt(0)
	v_cndmask_b32_e64 v98, v103, v132, s[42:43]
	v_pk_mul_f32 v[86:87], v[146:147], v[86:87]
	v_fma_f32 v98, v114, v98, v118
	v_add_f32_e32 v87, v87, v98
	v_add_f32_e32 v86, v86, v87
	v_mul_f32_e32 v87, 0xbfb8aa3b, v86
	v_exp_f32_e32 v87, v87
	v_add_f32_e32 v89, 1.0, v89
	v_rcp_f32_e32 v89, v89
	v_rsq_f32_e32 v92, v92
	v_add_f32_e32 v87, 1.0, v87
	v_rcp_f32_e32 v87, v87
	v_pk_mul_f32 v[82:83], v[82:83], v[94:95] op_sel_hi:[1,0]
	v_mul_f32_e32 v96, v99, v96
	v_mul_f32_e32 v88, v88, v89
	v_mul_f32_e32 v86, v86, v87
	v_mul_f32_e32 v84, v84, v96
	v_mul_f32_e32 v83, v83, v88
	v_mul_f32_e32 v82, v82, v86
	v_cvt_pk_bf16_f32 v82, v82, v83
	v_cvt_pk_bf16_f32 v83, v84, v85
	v_mov_b64_e32 v[84:85], s[48:49]
	v_mad_i64_i32 v[86:87], s[10:11], v95, s17, v[84:85]
	v_pk_mul_f32 v[80:81], v[80:81], v[92:93] op_sel_hi:[1,0]
	v_lshl_add_u64 v[98:99], v[86:87], 0, v[124:125]
	s_nop 1
	v_mov_b32_dpp v87, v81 row_ror:1 row_mask:0xf bank_mask:0xf
	v_mov_b32_dpp v95, v81 row_ror:2 row_mask:0xf bank_mask:0xf
	v_mov_b32_e32 v214, v82
	v_mov_b32_e32 v215, v83
	v_mov_b32_e32 v82, v81
	v_pk_mul_f32 v[78:79], v[78:79], v[92:93] op_sel_hi:[1,0]
	s_waitcnt lgkmcnt(1)
	v_cndmask_b32_e64 v83, v87, v131, s[40:41]
	s_waitcnt lgkmcnt(0)
	v_cndmask_b32_e64 v81, v138, v95, s[42:43]
	v_pk_mul_f32 v[82:83], v[126:127], v[82:83]
	v_fma_f32 v81, v117, v81, v121
	v_add_f32_e32 v81, v83, v81
	v_add_f32_e32 v82, v82, v81
	v_mul_f32_e32 v81, 0xbfb8aa3b, v82
	v_exp_f32_e32 v81, v81
	v_mov_b32_dpp v83, v80 row_ror:1 row_mask:0xf bank_mask:0xf
	v_mov_b32_dpp v131, v80 row_ror:2 row_mask:0xf bank_mask:0xf
	v_mov_b32_dpp v89, v79 row_ror:1 row_mask:0xf bank_mask:0xf
	v_add_f32_e32 v81, 1.0, v81
	v_rcp_f32_e32 v96, v81
	s_waitcnt lgkmcnt(2)
	v_cndmask_b32_e64 v81, v83, v97, s[40:41]
	s_waitcnt lgkmcnt(1)
	v_cndmask_b32_e64 v97, v140, v131, s[42:43]
	v_pk_mul_f32 v[80:81], v[148:149], v[80:81]
	v_fma_f32 v97, v116, v97, v120
	v_add_f32_e32 v81, v81, v97
	v_add_f32_e32 v97, v80, v81
	v_mul_f32_e32 v80, 0xbfb8aa3b, v97
	v_mov_b32_dpp v103, v79 row_ror:2 row_mask:0xf bank_mask:0xf
	v_exp_f32_e32 v80, v80
	v_pk_mul_f32 v[76:77], v[76:77], v[92:93] op_sel_hi:[1,0]
	v_mul_f32_e32 v81, v82, v96
	v_mov_b32_dpp v86, v78 row_ror:1 row_mask:0xf bank_mask:0xf
	v_add_f32_e32 v80, 1.0, v80
	v_mov_b32_dpp v88, v78 row_ror:2 row_mask:0xf bank_mask:0xf
	v_mul_f32_e32 v77, v77, v81
	v_rcp_f32_e32 v82, v80
	s_waitcnt lgkmcnt(3)
	v_cndmask_b32_e64 v81, v89, v133, s[40:41]
	v_mov_b32_e32 v80, v79
	s_waitcnt lgkmcnt(2)
	v_cndmask_b32_e64 v79, v139, v103, s[42:43]
	v_pk_mul_f32 v[80:81], v[128:129], v[80:81]
	v_fma_f32 v79, v115, v79, v119
	v_add_f32_e32 v79, v81, v79
	v_add_f32_e32 v80, v80, v79
	v_mul_f32_e32 v79, 0xbfb8aa3b, v80
	v_pk_mul_f32 v[74:75], v[74:75], v[92:93] op_sel_hi:[1,0]
	v_exp_f32_e32 v81, v79
	s_waitcnt lgkmcnt(1)
; __device__ __forceinline__ unsigned cvt_pk_bf16(float lo, float hi) { unsigned r; asm volatile("v_cvt_pk_bf16_f32 %0, %1, %2" : "=v"(r) : "v"(lo), "v"(hi)); return r; }
;     __device__ __forceinline__ void operator()(const f32x4 (&acc)[2][2][4][2], const Unit& u, int wr, int wc, int fr, int fq) const {
;     ...
;                     const f32x4 g = acc[ai][1][m][n] * rs[ai][m], v = acc[ai][0][m][n] * rs[ai][m];
;                     f32x4 r1, r2, a;
; #pragma unroll
;                     for (int e = 0; e < 4; ++e) { r1[e] = __shfl(g[e], src1); r2[e] = __shfl(g[e], src2); }
; #pragma unroll
;                     for (int e = 0; e < 4; ++e) {
;                         const float p1 = fr >= 1 ? r1[e] : r1p[e], p2 = fr >= 2 ? r2[e] : r2p[e];
;                         const float gg = b4[e] + w0[e] * p2 + w1[e] * p1 + w2[e] * g[e];
;                         a[e] = gg * __builtin_amdgcn_rcpf(1.f + __expf(-gg)) * v[e];
;                     }
;                     r1p = r1; r2p = r2;
;                     const size_t row = (size_t)(u.pm * BM + ai * HALF + wr * 64 + m * 16 + fr);
;                     if (m == 0 && fr < 2) {
;                         *(f32x4*)(GF + (size_t)(slab * 2 + fr) * FF + cbase) = g; *(f32x4*)(VF + (size_t)(slab * 2 + fr) * FF + cbase) = v;
;                     } else {
;                         typedef unsigned u32x2v __attribute__((ext_vector_type(2)));
;                         u32x2v w; w.x = cvt_pk_bf16(a[0], a[1]); w.y = cvt_pk_bf16(a[2], a[3]);
;                         *(u32x2v*)(ACT + row * FF + cbase) = w;
;                     }
;                     if (m == 3 && fr >= 14) *(f32x4*)(GL + (size_t)(slab * 2 + fr - 14) * FF + cbase) = g;
	v_cndmask_b32_e64 v79, v86, v93, s[40:41]
	s_waitcnt lgkmcnt(0)
	v_cndmask_b32_e64 v93, v132, v88, s[42:43]
	v_pk_mul_f32 v[78:79], v[146:147], v[78:79]
	v_fma_f32 v93, v114, v93, v118
	v_add_f32_e32 v79, v79, v93
	v_add_f32_e32 v78, v78, v79
	v_mul_f32_e32 v79, 0xbfb8aa3b, v78
	v_exp_f32_e32 v79, v79
	v_add_f32_e32 v81, 1.0, v81
	v_rcp_f32_e32 v81, v81
	v_fmamk_f32 v90, v90, 0x31000000, v232
	v_add_f32_e32 v79, 1.0, v79
	v_rcp_f32_e32 v79, v79
	v_rsq_f32_e32 v90, v90
	v_mul_f32_e32 v82, v97, v82
	v_mul_f32_e32 v80, v80, v81
	v_mul_f32_e32 v78, v78, v79
	v_add_u32_e32 v130, 0xa0, v160
	v_mul_f32_e32 v76, v76, v82
	v_mul_f32_e32 v75, v75, v80
	v_mul_f32_e32 v74, v74, v78
	v_add_u32_e32 v91, 0xb0, v160
	v_cvt_pk_bf16_f32 v74, v74, v75
	v_cvt_pk_bf16_f32 v75, v76, v77
	v_mad_i64_i32 v[76:77], s[10:11], v130, s17, v[84:85]
	v_lshl_add_u64 v[96:97], v[76:77], 0, v[124:125]
	v_pk_mul_f32 v[72:73], v[72:73], v[90:91] op_sel_hi:[1,0]
	v_mov_b32_e32 v216, v74
	v_mov_b32_e32 v217, v75
	v_mov_b32_dpp v74, v73 row_ror:1 row_mask:0xf bank_mask:0xf
	v_mov_b32_dpp v79, v73 row_ror:2 row_mask:0xf bank_mask:0xf
	v_mov_b32_dpp v81, v72 row_ror:2 row_mask:0xf bank_mask:0xf
	v_pk_mul_f32 v[70:71], v[70:71], v[90:91] op_sel_hi:[1,0]
	s_nop 1
	v_mov_b32_dpp v78, v71 row_ror:1 row_mask:0xf bank_mask:0xf
	s_waitcnt lgkmcnt(3)
	v_cndmask_b32_e64 v75, v74, v87, s[40:41]
	v_mov_b32_e32 v74, v73
	s_waitcnt lgkmcnt(2)
	v_cndmask_b32_e64 v79, v95, v79, s[42:43]
	v_pk_mul_f32 v[74:75], v[126:127], v[74:75]
	v_fma_f32 v79, v117, v79, v121
	v_add_f32_e32 v75, v75, v79
	v_add_f32_e32 v79, v74, v75
	v_mul_f32_e32 v74, 0xbfb8aa3b, v79
	v_exp_f32_e32 v74, v74
	v_mov_b32_dpp v75, v72 row_ror:1 row_mask:0xf bank_mask:0xf
	s_waitcnt lgkmcnt(2)
	v_cndmask_b32_e64 v81, v131, v81, s[42:43]
	v_fma_f32 v81, v116, v81, v120
	v_add_f32_e32 v74, 1.0, v74
	v_rcp_f32_e32 v82, v74
	s_waitcnt lgkmcnt(0)
	v_cndmask_b32_e64 v75, v75, v83, s[40:41]
	v_mov_b32_e32 v74, v72
	v_pk_mul_f32 v[74:75], v[148:149], v[74:75]
	v_mov_b32_dpp v80, v71 row_ror:2 row_mask:0xf bank_mask:0xf
	v_add_f32_e32 v75, v75, v81
	v_add_f32_e32 v81, v74, v75
	v_mul_f32_e32 v74, 0xbfb8aa3b, v81
	v_exp_f32_e32 v74, v74
	v_pk_mul_f32 v[68:69], v[68:69], v[90:91] op_sel_hi:[1,0]
	v_mul_f32_e32 v75, v79, v82
	v_mov_b32_dpp v76, v70 row_ror:1 row_mask:0xf bank_mask:0xf
	v_add_f32_e32 v74, 1.0, v74
	v_mov_b32_dpp v77, v70 row_ror:2 row_mask:0xf bank_mask:0xf
	v_mul_f32_e32 v69, v69, v75
	v_rcp_f32_e32 v79, v74
	v_cndmask_b32_e64 v75, v78, v89, s[40:41]
	v_mov_b32_e32 v74, v71
	s_waitcnt lgkmcnt(2)
	v_cndmask_b32_e64 v78, v103, v80, s[42:43]
	v_pk_mul_f32 v[74:75], v[128:129], v[74:75]
	v_fma_f32 v78, v115, v78, v119
	v_add_f32_e32 v75, v75, v78
	v_add_f32_e32 v78, v74, v75
	v_mul_f32_e32 v74, 0xbfb8aa3b, v78
	v_exp_f32_e32 v80, v74
	s_waitcnt lgkmcnt(1)
	v_cndmask_b32_e64 v75, v76, v86, s[40:41]
	v_mov_b32_e32 v74, v70
	s_waitcnt lgkmcnt(0)
	v_cndmask_b32_e64 v76, v88, v77, s[42:43]
	v_pk_mul_f32 v[74:75], v[146:147], v[74:75]
	v_fmac_f32_e32 v118, v114, v76
	v_add_f32_e32 v75, v75, v118
	v_add_f32_e32 v74, v74, v75
	v_mul_f32_e32 v75, 0xbfb8aa3b, v74
	v_exp_f32_e32 v75, v75
	v_add_f32_e32 v77, 1.0, v80
	v_rcp_f32_e32 v77, v77
	v_mul_f32_e32 v76, v81, v79
	v_add_f32_e32 v75, 1.0, v75
	v_rcp_f32_e32 v75, v75
	v_pk_mul_f32 v[66:67], v[66:67], v[90:91] op_sel_hi:[1,0]
	v_mul_f32_e32 v68, v68, v76
	v_mul_f32_e32 v76, v78, v77
	v_mul_f32_e32 v74, v74, v75
	v_mul_f32_e32 v67, v67, v76
	v_mul_f32_e32 v66, v66, v74
	v_cvt_pk_bf16_f32 v66, v66, v67
	v_cvt_pk_bf16_f32 v67, v68, v69
	v_mad_i64_i32 v[68:69], s[10:11], v91, s17, v[84:85]
	v_readlane_b32 s10, v254, 44
	v_lshl_add_u64 v[88:89], v[68:69], 0, v[124:125]
	v_readlane_b32 s11, v254, 45
	v_mov_b32_e32 v218, v66
	v_mov_b32_e32 v219, v67
	s_nop 0
	v_lshl_add_u64 v[66:67], s[10:11], 0, v[100:101]
	v_lshl_add_u64 v[86:87], v[156:157], 2, v[66:67]
	s_and_saveexec_b64 s[10:11], s[44:45]
	s_cbranch_execz .LBB0_53
	global_store_dwordx4 v[86:87], v[70:73], off
; __device__ __forceinline__ unsigned cvt_pk_bf16(float lo, float hi) { unsigned r; asm volatile("v_cvt_pk_bf16_f32 %0, %1, %2" : "=v"(r) : "v"(lo), "v"(hi)); return r; }
;     __device__ __forceinline__ void operator()(const f32x4 (&acc)[2][2][4][2], const Unit& u, int wr, int wc, int fr, int fq) const {
;     ...
;             const int cbase = 128 * u.pn + 32 * wc + 16 * n + 4 * fq;
;             const f32x4 w0 = *(const f32x4*)(cw + cbase), w1 = *(const f32x4*)(cw + FF + cbase), w2 = *(const f32x4*)(cw + 2 * FF + cbase), b4 = *(const f32x4*)(cb + cbase);
; #pragma unroll
;             for (int ai = 0; ai < 2; ++ai) {
;                 const int slab = u.pm * 4 + 2 * ai + wr;
;                 f32x4 r1p = (f32x4){0.f, 0.f, 0.f, 0.f}, r2p = (f32x4){0.f, 0.f, 0.f, 0.f};
; #pragma unroll
;                 for (int m = 0; m < 4; ++m) {
;                     const f32x4 g = acc[ai][1][m][n] * rs[ai][m], v = acc[ai][0][m][n] * rs[ai][m];
;                     f32x4 r1, r2, a;
; #pragma unroll
;                     for (int e = 0; e < 4; ++e) { r1[e] = __shfl(g[e], src1); r2[e] = __shfl(g[e], src2); }
; #pragma unroll
;                     for (int e = 0; e < 4; ++e) {
;                         const float p1 = fr >= 1 ? r1[e] : r1p[e], p2 = fr >= 2 ? r2[e] : r2p[e];
;                         const float gg = b4[e] + w0[e] * p2 + w1[e] * p1 + w2[e] * g[e];
;                         a[e] = gg * __builtin_amdgcn_rcpf(1.f + __expf(-gg)) * v[e];
;                     }
;                     r1p = r1; r2p = r2;
;                     const size_t row = (size_t)(u.pm * BM + ai * HALF + wr * 64 + m * 16 + fr);
;                     if (m == 0 && fr < 2) {
;                         *(f32x4*)(GF + (size_t)(slab * 2 + fr) * FF + cbase) = g; *(f32x4*)(VF + (size_t)(slab * 2 + fr) * FF + cbase) = v;
;                     } else {
;                         typedef unsigned u32x2v __attribute__((ext_vector_type(2)));
;                         u32x2v w; w.x = cvt_pk_bf16(a[0], a[1]); w.y = cvt_pk_bf16(a[2], a[3]);
;                         *(u32x2v*)(ACT + row * FF + cbase) = w;
.LBB0_53:
	s_or_b64 exec, exec, s[10:11]
	s_nop 0
	v_or_b32_e32 v70, 16, v156
	v_ashrrev_i32_e32 v71, 31, v70
	v_lshlrev_b64 v[70:71], 2, v[70:71]
	v_lshl_add_u64 v[72:73], s[60:61], 0, v[70:71]
	v_lshl_add_u64 v[70:71], s[62:63], 0, v[70:71]
	global_load_dwordx4 v[66:69], v[166:167], off offset:64
	global_load_dwordx4 v[78:81], v[72:73], off
	global_load_dwordx4 v[74:77], v[70:71], off
	s_nop 0
	global_load_dwordx4 v[70:73], v[164:165], off offset:64
	v_mov_b32_e32 v163, v162
	v_mov_b32_e32 v120, v162
	v_mov_b32_e32 v121, v162
	v_pk_mul_f32 v[84:85], v[60:61], v[120:121]
	v_pk_mul_f32 v[82:83], v[58:59], v[162:163]
	s_nop 1
	v_mov_b32_dpp v101, v82 row_ror:1 row_mask:0xf bank_mask:0xf
	v_mov_b32_dpp v91, v82 row_ror:2 row_mask:0xf bank_mask:0xf
	v_mov_b32_dpp v115, v83 row_ror:1 row_mask:0xf bank_mask:0xf
	v_mov_b32_dpp v93, v83 row_ror:2 row_mask:0xf bank_mask:0xf
	v_mov_b32_dpp v117, v84 row_ror:1 row_mask:0xf bank_mask:0xf
	v_mov_b32_dpp v95, v84 row_ror:2 row_mask:0xf bank_mask:0xf
	v_mov_b32_dpp v119, v85 row_ror:1 row_mask:0xf bank_mask:0xf
	v_mov_b32_dpp v103, v85 row_ror:2 row_mask:0xf bank_mask:0xf
	v_pk_mul_f32 v[60:61], v[64:65], v[120:121]
	v_pk_mul_f32 v[58:59], v[62:63], v[162:163]
	s_and_saveexec_b64 s[10:11], s[42:43]
	s_xor_b64 s[10:11], exec, s[10:11]
	s_cbranch_execz .LBB0_55
	v_mov_b32_e32 v62, v85
	s_waitcnt vmcnt(2)
	v_mov_b32_e32 v63, v81
	s_waitcnt vmcnt(1)
	v_mov_b32_e32 v118, v77
	s_waitcnt lgkmcnt(1)
	v_pk_mul_f32 v[62:63], v[62:63], v[118:119]
	s_waitcnt vmcnt(0) lgkmcnt(0)
	v_fma_f32 v64, v69, v103, v73
	v_add_f32_e32 v63, v63, v64
	v_add_f32_e32 v62, v62, v63
	v_mul_f32_e32 v63, 0xbfb8aa3b, v62
	v_exp_f32_e32 v63, v63
	v_mov_b32_e32 v85, v80
	v_mov_b32_e32 v116, v76
	v_mov_b32_e32 v114, v75
	v_add_f32_e32 v63, 1.0, v63
	v_rcp_f32_e32 v63, v63
	v_mov_b32_e32 v100, v74
	v_mul_f32_e32 v62, v62, v63
	v_mul_f32_e32 v64, v61, v62
	v_pk_mul_f32 v[62:63], v[84:85], v[116:117]
	v_fma_f32 v61, v68, v95, v72
	v_add_f32_e32 v61, v63, v61
	v_add_f32_e32 v61, v62, v61
	v_mul_f32_e32 v62, 0xbfb8aa3b, v61
	v_exp_f32_e32 v62, v62
	v_fma_f32 v63, v67, v93, v71
	v_add_f32_e32 v62, 1.0, v62
	v_rcp_f32_e32 v62, v62
	s_nop 0
	v_mul_f32_e32 v61, v61, v62
	v_mul_f32_e32 v62, v60, v61
	v_mov_b32_e32 v60, v83
	v_mov_b32_e32 v61, v79
	v_pk_mul_f32 v[60:61], v[60:61], v[114:115]
	v_mov_b32_e32 v83, v78
	v_add_f32_e32 v61, v61, v63
	v_add_f32_e32 v60, v60, v61
	v_mul_f32_e32 v61, 0xbfb8aa3b, v60
	v_exp_f32_e32 v61, v61
	v_fma_f32 v63, v66, v91, v70
	v_add_f32_e32 v61, 1.0, v61
	v_rcp_f32_e32 v61, v61
	s_nop 0
	v_mul_f32_e32 v60, v60, v61
	v_mul_f32_e32 v59, v59, v60
	v_pk_mul_f32 v[60:61], v[82:83], v[100:101]
	s_nop 0
	v_add_f32_e32 v61, v61, v63
	v_add_f32_e32 v60, v60, v61
	v_mul_f32_e32 v61, 0xbfb8aa3b, v60
	v_exp_f32_e32 v61, v61
	s_nop 0
	v_add_f32_e32 v61, 1.0, v61
	v_rcp_f32_e32 v61, v61
	s_nop 0
	v_mul_f32_e32 v60, v60, v61
	v_mul_f32_e32 v58, v58, v60
	v_mov_b64_e32 v[60:61], s[48:49]
	v_mad_i64_i32 v[60:61], s[12:13], v160, s17, v[60:61]
	v_cvt_pk_bf16_f32 v58, v58, v59
	v_cvt_pk_bf16_f32 v59, v62, v64
	v_lshl_add_u64 v[60:61], v[156:157], 1, v[60:61]
	v_mov_b32_e32 v64, v77
	v_mov_b32_e32 v62, v75
	s_nop 1
	v_permlane16_swap_b32_e32 v220, v58
	v_permlane16_swap_b32_e32 v221, v59
	v_mov_b32_e32 v222, v58
	v_mov_b32_e32 v223, v59
	v_add_co_u32_e64 v60, s[98:99], v60, v205
	s_nop 1
	v_addc_co_u32_e64 v61, s[98:99], 0, v61, s[98:99]
	global_store_dwordx4 v[60:61], v[220:223], off

; __device__ __forceinline__ unsigned cvt_pk_bf16(float lo, float hi) { unsigned r; asm volatile("v_cvt_pk_bf16_f32 %0, %1, %2" : "=v"(r) : "v"(lo), "v"(hi)); return r; }
;     __device__ __forceinline__ void operator()(const f32x4 (&acc)[2][2][4][2], const Unit& u, int wr, int wc, int fr, int fq) const {
;     ...
;                     const f32x4 g = acc[ai][1][m][n] * rs[ai][m], v = acc[ai][0][m][n] * rs[ai][m];
;                     f32x4 r1, r2, a;
; #pragma unroll
;                     for (int e = 0; e < 4; ++e) { r1[e] = __shfl(g[e], src1); r2[e] = __shfl(g[e], src2); }
; #pragma unroll
;                     for (int e = 0; e < 4; ++e) {
;                         const float p1 = fr >= 1 ? r1[e] : r1p[e], p2 = fr >= 2 ? r2[e] : r2p[e];
;                         const float gg = b4[e] + w0[e] * p2 + w1[e] * p1 + w2[e] * g[e];
;                         a[e] = gg * __builtin_amdgcn_rcpf(1.f + __expf(-gg)) * v[e];
;                     }
;                     r1p = r1; r2p = r2;
;                     const size_t row = (size_t)(u.pm * BM + ai * HALF + wr * 64 + m * 16 + fr);
;                     if (m == 0 && fr < 2) {
;                         *(f32x4*)(GF + (size_t)(slab * 2 + fr) * FF + cbase) = g; *(f32x4*)(VF + (size_t)(slab * 2 + fr) * FF + cbase) = v;
;                     } else {
;                         typedef unsigned u32x2v __attribute__((ext_vector_type(2)));
;                         u32x2v w; w.x = cvt_pk_bf16(a[0], a[1]); w.y = cvt_pk_bf16(a[2], a[3]);
;                         *(u32x2v*)(ACT + row * FF + cbase) = w;
.LBB0_57:
	s_or_b64 exec, exec, s[10:11]
	v_mov_b32_e32 v58, v142
	v_mov_b32_e32 v59, v142
	v_pk_mul_f32 v[56:57], v[56:57], v[58:59]
	s_nop 1
	v_mov_b32_dpp v83, v57 row_ror:1 row_mask:0xf bank_mask:0xf
	v_mov_b32_dpp v114, v57 row_ror:2 row_mask:0xf bank_mask:0xf
	v_mov_b32_e32 v60, v57
	s_waitcnt vmcnt(2)
	v_mov_b32_e32 v61, v81
	v_pk_mul_f32 v[52:53], v[52:53], v[58:59]
	s_waitcnt lgkmcnt(1)
	v_cndmask_b32_e64 v65, v83, v119, s[40:41]
	s_waitcnt lgkmcnt(0)
	v_cndmask_b32_e64 v57, v103, v114, s[42:43]
	v_pk_mul_f32 v[60:61], v[60:61], v[64:65]
	s_waitcnt vmcnt(0)
	v_fma_f32 v57, v69, v57, v73
	v_add_f32_e32 v57, v61, v57
	v_add_f32_e32 v60, v60, v57
	v_mul_f32_e32 v57, 0xbfb8aa3b, v60
	v_exp_f32_e32 v57, v57
	v_mov_b32_dpp v61, v56 row_ror:1 row_mask:0xf bank_mask:0xf
	v_mov_b32_dpp v103, v56 row_ror:2 row_mask:0xf bank_mask:0xf
	v_mov_b32_e32 v143, v142
	v_add_f32_e32 v57, 1.0, v57
	v_rcp_f32_e32 v58, v57
	s_waitcnt lgkmcnt(1)
	v_cndmask_b32_e64 v77, v61, v117, s[40:41]
	v_mov_b32_e32 v57, v80
	s_waitcnt lgkmcnt(0)
	v_cndmask_b32_e64 v59, v95, v103, s[42:43]
	v_pk_mul_f32 v[56:57], v[56:57], v[76:77]
	v_fma_f32 v59, v68, v59, v72
	v_add_f32_e32 v57, v57, v59
	v_add_f32_e32 v59, v56, v57
	v_pk_mul_f32 v[54:55], v[54:55], v[142:143]
	v_mul_f32_e32 v56, 0xbfb8aa3b, v59
	s_nop 1
	v_mov_b32_dpp v85, v55 row_ror:1 row_mask:0xf bank_mask:0xf
	v_mov_b32_dpp v100, v55 row_ror:2 row_mask:0xf bank_mask:0xf
	v_exp_f32_e32 v56, v56
	v_mul_f32_e32 v57, v60, v58
	v_mov_b32_dpp v82, v54 row_ror:1 row_mask:0xf bank_mask:0xf
	v_mov_b32_dpp v84, v54 row_ror:2 row_mask:0xf bank_mask:0xf
	v_add_f32_e32 v56, 1.0, v56
	v_mul_f32_e32 v53, v53, v57
	v_rcp_f32_e32 v58, v56
	s_waitcnt lgkmcnt(3)
	v_cndmask_b32_e64 v63, v85, v115, s[40:41]
	v_mov_b32_e32 v56, v55
	v_mov_b32_e32 v57, v79
	s_waitcnt lgkmcnt(2)
	v_cndmask_b32_e64 v55, v93, v100, s[42:43]
	v_pk_mul_f32 v[56:57], v[56:57], v[62:63]
	v_fma_f32 v55, v67, v55, v71
	v_add_f32_e32 v55, v57, v55
	v_add_f32_e32 v56, v56, v55
	v_mul_f32_e32 v55, 0xbfb8aa3b, v56
	v_exp_f32_e32 v57, v55
	s_waitcnt lgkmcnt(1)
	v_cndmask_b32_e64 v75, v82, v101, s[40:41]
	v_mov_b32_e32 v55, v78
	s_waitcnt lgkmcnt(0)
	v_cndmask_b32_e64 v60, v91, v84, s[42:43]
	v_pk_mul_f32 v[54:55], v[54:55], v[74:75]
	v_fma_f32 v60, v66, v60, v70
	v_add_f32_e32 v55, v55, v60
	v_add_f32_e32 v54, v54, v55
	v_mul_f32_e32 v55, 0xbfb8aa3b, v54
	v_exp_f32_e32 v55, v55
	v_add_f32_e32 v57, 1.0, v57
	v_rcp_f32_e32 v57, v57
	v_pk_mul_f32 v[50:51], v[50:51], v[142:143]
	v_add_f32_e32 v55, 1.0, v55
	v_rcp_f32_e32 v55, v55
	v_mul_f32_e32 v56, v56, v57
	v_mul_f32_e32 v58, v59, v58
	v_mul_f32_e32 v51, v51, v56
	v_mul_f32_e32 v54, v54, v55
	v_mul_f32_e32 v50, v50, v54
	v_mul_f32_e32 v52, v52, v58
	v_cvt_pk_bf16_f32 v50, v50, v51
	v_cvt_pk_bf16_f32 v51, v52, v53
	s_nop 1
	v_permlane16_swap_b32_e32 v206, v50
	v_permlane16_swap_b32_e32 v207, v51
	v_mov_b32_e32 v220, v206
	v_mov_b32_e32 v221, v207
	v_mov_b32_e32 v222, v50
	v_mov_b32_e32 v223, v51
	v_add_co_u32_e64 v122, s[98:99], v122, v205
	s_nop 1
	v_addc_co_u32_e64 v123, s[98:99], 0, v123, s[98:99]
	global_store_dwordx4 v[122:123], v[220:223], off
	v_mov_b32_e32 v50, v136
	v_mov_b32_e32 v51, v136
	v_pk_mul_f32 v[48:49], v[48:49], v[50:51]
	s_nop 1
	v_mov_b32_dpp v55, v49 row_ror:1 row_mask:0xf bank_mask:0xf
	v_mov_b32_dpp v59, v49 row_ror:2 row_mask:0xf bank_mask:0xf
	v_mov_b32_e32 v52, v49
	v_mov_b32_e32 v53, v81
	v_mov_b32_dpp v60, v48 row_ror:2 row_mask:0xf bank_mask:0xf
	s_waitcnt lgkmcnt(2)
	v_cndmask_b32_e64 v65, v55, v83, s[40:41]
	s_waitcnt lgkmcnt(1)
	v_cndmask_b32_e64 v49, v114, v59, s[42:43]
	v_pk_mul_f32 v[52:53], v[52:53], v[64:65]
	v_fma_f32 v49, v69, v49, v73
	v_add_f32_e32 v49, v53, v49
	v_add_f32_e32 v52, v52, v49
	v_mul_f32_e32 v49, 0xbfb8aa3b, v52
	v_exp_f32_e32 v49, v49
	v_mov_b32_dpp v53, v48 row_ror:1 row_mask:0xf bank_mask:0xf
	v_pk_mul_f32 v[44:45], v[44:45], v[50:51]
	s_waitcnt lgkmcnt(1)
	v_cndmask_b32_e64 v51, v103, v60, s[42:43]
	v_add_f32_e32 v49, 1.0, v49
	v_rcp_f32_e32 v50, v49
	s_waitcnt lgkmcnt(0)
	v_cndmask_b32_e64 v77, v53, v61, s[40:41]
	v_mov_b32_e32 v49, v80
	v_pk_mul_f32 v[48:49], v[48:49], v[76:77]
	v_fma_f32 v51, v68, v51, v72
	v_add_f32_e32 v49, v49, v51
	v_mov_b32_e32 v137, v136
	v_add_f32_e32 v51, v48, v49
	v_pk_mul_f32 v[46:47], v[46:47], v[136:137]
	v_mul_f32_e32 v48, 0xbfb8aa3b, v51
	s_nop 1
	v_mov_b32_dpp v57, v47 row_ror:1 row_mask:0xf bank_mask:0xf
	v_mov_b32_dpp v58, v47 row_ror:2 row_mask:0xf bank_mask:0xf
	v_exp_f32_e32 v48, v48
	v_mul_f32_e32 v49, v52, v50
	v_mov_b32_dpp v54, v46 row_ror:1 row_mask:0xf bank_mask:0xf
	v_mov_b32_dpp v56, v46 row_ror:2 row_mask:0xf bank_mask:0xf
	v_add_f32_e32 v48, 1.0, v48
	v_mul_f32_e32 v45, v45, v49
	v_rcp_f32_e32 v50, v48
	s_waitcnt lgkmcnt(3)
	v_cndmask_b32_e64 v63, v57, v85, s[40:41]
	v_mov_b32_e32 v48, v47
	v_mov_b32_e32 v49, v79
	s_waitcnt lgkmcnt(2)
	v_cndmask_b32_e64 v47, v100, v58, s[42:43]
	v_pk_mul_f32 v[48:49], v[48:49], v[62:63]
	v_fma_f32 v47, v67, v47, v71
	v_add_f32_e32 v47, v49, v47
	v_add_f32_e32 v48, v48, v47
	v_mul_f32_e32 v47, 0xbfb8aa3b, v48
	v_exp_f32_e32 v49, v47
	s_waitcnt lgkmcnt(1)
	v_cndmask_b32_e64 v75, v54, v82, s[40:41]
	v_mov_b32_e32 v47, v78
	s_waitcnt lgkmcnt(0)
; __device__ __forceinline__ unsigned cvt_pk_bf16(float lo, float hi) { unsigned r; asm volatile("v_cvt_pk_bf16_f32 %0, %1, %2" : "=v"(r) : "v"(lo), "v"(hi)); return r; }
;     __device__ __forceinline__ void operator()(const f32x4 (&acc)[2][2][4][2], const Unit& u, int wr, int wc, int fr, int fq) const {
;     ...
;                     const f32x4 g = acc[ai][1][m][n] * rs[ai][m], v = acc[ai][0][m][n] * rs[ai][m];
;                     f32x4 r1, r2, a;
; #pragma unroll
;                     for (int e = 0; e < 4; ++e) { r1[e] = __shfl(g[e], src1); r2[e] = __shfl(g[e], src2); }
; #pragma unroll
;                     for (int e = 0; e < 4; ++e) {
;                         const float p1 = fr >= 1 ? r1[e] : r1p[e], p2 = fr >= 2 ? r2[e] : r2p[e];
;                         const float gg = b4[e] + w0[e] * p2 + w1[e] * p1 + w2[e] * g[e];
;                         a[e] = gg * __builtin_amdgcn_rcpf(1.f + __expf(-gg)) * v[e];
;                     }
;                     r1p = r1; r2p = r2;
;                     const size_t row = (size_t)(u.pm * BM + ai * HALF + wr * 64 + m * 16 + fr);
;                     if (m == 0 && fr < 2) {
;                         *(f32x4*)(GF + (size_t)(slab * 2 + fr) * FF + cbase) = g; *(f32x4*)(VF + (size_t)(slab * 2 + fr) * FF + cbase) = v;
;                     } else {
;                         typedef unsigned u32x2v __attribute__((ext_vector_type(2)));
;                         u32x2v w; w.x = cvt_pk_bf16(a[0], a[1]); w.y = cvt_pk_bf16(a[2], a[3]);
;                         *(u32x2v*)(ACT + row * FF + cbase) = w;
;                     }
;                     if (m == 3 && fr >= 14) *(f32x4*)(GL + (size_t)(slab * 2 + fr - 14) * FF + cbase) = g;
	v_cndmask_b32_e64 v52, v84, v56, s[42:43]
	v_pk_mul_f32 v[46:47], v[46:47], v[74:75]
	v_fma_f32 v52, v66, v52, v70
	v_add_f32_e32 v47, v47, v52
	v_add_f32_e32 v46, v46, v47
	v_mul_f32_e32 v47, 0xbfb8aa3b, v46
	v_exp_f32_e32 v47, v47
	v_add_f32_e32 v49, 1.0, v49
	v_rcp_f32_e32 v49, v49
	v_pk_mul_f32 v[42:43], v[42:43], v[136:137]
	v_add_f32_e32 v47, 1.0, v47
	v_rcp_f32_e32 v47, v47
	v_mul_f32_e32 v48, v48, v49
	v_mul_f32_e32 v50, v51, v50
	v_mul_f32_e32 v43, v43, v48
	v_mul_f32_e32 v46, v46, v47
	v_mul_f32_e32 v42, v42, v46
	v_mul_f32_e32 v44, v44, v50
	v_cvt_pk_bf16_f32 v42, v42, v43
	v_cvt_pk_bf16_f32 v43, v44, v45
	s_nop 1
	v_permlane16_swap_b32_e32 v208, v42
	v_permlane16_swap_b32_e32 v209, v43
	v_mov_b32_e32 v220, v208
	v_mov_b32_e32 v221, v209
	v_mov_b32_e32 v222, v42
	v_mov_b32_e32 v223, v43
	v_add_co_u32_e64 v108, s[98:99], v108, v205
	s_nop 1
	v_addc_co_u32_e64 v109, s[98:99], 0, v109, s[98:99]
	global_store_dwordx4 v[108:109], v[220:223], off
	v_mov_b32_e32 v42, v134
	v_mov_b32_e32 v43, v134
	v_pk_mul_f32 v[40:41], v[40:41], v[42:43]
	s_nop 1
	v_mov_b32_dpp v44, v41 row_ror:1 row_mask:0xf bank_mask:0xf
	v_mov_b32_dpp v50, v41 row_ror:2 row_mask:0xf bank_mask:0xf
	v_mov_b32_e32 v45, v81
	v_mov_b32_dpp v51, v40 row_ror:2 row_mask:0xf bank_mask:0xf
	v_pk_mul_f32 v[36:37], v[36:37], v[42:43]
	s_waitcnt lgkmcnt(2)
	v_cndmask_b32_e64 v65, v44, v55, s[40:41]
	v_mov_b32_e32 v44, v41
	s_waitcnt lgkmcnt(1)
	v_cndmask_b32_e64 v50, v59, v50, s[42:43]
	v_pk_mul_f32 v[44:45], v[44:45], v[64:65]
	v_fma_f32 v50, v69, v50, v73
	v_add_f32_e32 v45, v45, v50
	v_add_f32_e32 v44, v44, v45
	v_mul_f32_e32 v45, 0xbfb8aa3b, v44
	v_exp_f32_e32 v45, v45
	v_mov_b32_dpp v50, v40 row_ror:1 row_mask:0xf bank_mask:0xf
	v_mov_b32_e32 v43, v80
	v_mov_b32_e32 v135, v134
	v_add_f32_e32 v42, 1.0, v45
	v_rcp_f32_e32 v45, v42
	s_waitcnt lgkmcnt(0)
	v_cndmask_b32_e64 v77, v50, v53, s[40:41]
	v_mov_b32_e32 v42, v40
	v_cndmask_b32_e64 v50, v60, v51, s[42:43]
	v_pk_mul_f32 v[42:43], v[42:43], v[76:77]
	v_fma_f32 v50, v68, v50, v72
	v_add_f32_e32 v43, v43, v50
	v_add_f32_e32 v50, v42, v43
	v_pk_mul_f32 v[38:39], v[38:39], v[134:135]
	v_mul_f32_e32 v42, 0xbfb8aa3b, v50
	s_nop 1
	v_mov_b32_dpp v48, v39 row_ror:1 row_mask:0xf bank_mask:0xf
	v_mov_b32_dpp v49, v39 row_ror:2 row_mask:0xf bank_mask:0xf
	v_exp_f32_e32 v42, v42
	v_mul_f32_e32 v43, v44, v45
	v_mov_b32_dpp v46, v38 row_ror:1 row_mask:0xf bank_mask:0xf
	v_mov_b32_dpp v47, v38 row_ror:2 row_mask:0xf bank_mask:0xf
	v_add_f32_e32 v42, 1.0, v42
	v_mul_f32_e32 v37, v37, v43
	v_rcp_f32_e32 v44, v42
	s_waitcnt lgkmcnt(3)
	v_cndmask_b32_e64 v63, v48, v57, s[40:41]
	v_mov_b32_e32 v42, v39
	v_mov_b32_e32 v43, v79
	s_waitcnt lgkmcnt(2)
	v_cndmask_b32_e64 v45, v58, v49, s[42:43]
	v_pk_mul_f32 v[42:43], v[42:43], v[62:63]
	v_fma_f32 v45, v67, v45, v71
	v_add_f32_e32 v43, v43, v45
	v_add_f32_e32 v45, v42, v43
	v_mul_f32_e32 v42, 0xbfb8aa3b, v45
	v_exp_f32_e32 v48, v42
	s_waitcnt lgkmcnt(1)
	v_cndmask_b32_e64 v75, v46, v54, s[40:41]
	v_mov_b32_e32 v42, v38
	v_mov_b32_e32 v43, v78
	s_waitcnt lgkmcnt(0)
	v_cndmask_b32_e64 v46, v56, v47, s[42:43]
	v_pk_mul_f32 v[42:43], v[42:43], v[74:75]
	v_fma_f32 v46, v66, v46, v70
	v_add_f32_e32 v43, v43, v46
	v_add_f32_e32 v42, v42, v43
	v_mul_f32_e32 v43, 0xbfb8aa3b, v42
	v_exp_f32_e32 v43, v43
	v_add_f32_e32 v46, 1.0, v48
	v_rcp_f32_e32 v46, v46
	v_mul_f32_e32 v44, v50, v44
	v_add_f32_e32 v43, 1.0, v43
	v_rcp_f32_e32 v43, v43
	v_pk_mul_f32 v[34:35], v[34:35], v[134:135]
	v_mul_f32_e32 v36, v36, v44
	v_mul_f32_e32 v44, v45, v46
	v_mul_f32_e32 v42, v42, v43
	v_mul_f32_e32 v35, v35, v44
	v_mul_f32_e32 v34, v34, v42
	v_cvt_pk_bf16_f32 v34, v34, v35
	v_cvt_pk_bf16_f32 v35, v36, v37
	s_nop 1
	v_permlane16_swap_b32_e32 v210, v34
	v_permlane16_swap_b32_e32 v211, v35
	v_mov_b32_e32 v220, v210
	v_mov_b32_e32 v221, v211
	v_mov_b32_e32 v222, v34
	v_mov_b32_e32 v223, v35
	v_add_co_u32_e64 v110, s[98:99], v110, v205
	s_nop 1
	v_addc_co_u32_e64 v111, s[98:99], 0, v111, s[98:99]
	global_store_dwordx4 v[110:111], v[220:223], off
	s_and_saveexec_b64 s[10:11], s[44:45]
	s_cbranch_execz .LBB0_59
	global_store_dwordx4 v[106:107], v[38:41], off offset:64
.LBB0_59:
	s_or_b64 exec, exec, s[10:11]
	v_mov_b32_e32 v103, v102
	v_mov_b32_e32 v42, v102
	v_mov_b32_e32 v43, v102
	v_pk_mul_f32 v[36:37], v[28:29], v[42:43]
	v_pk_mul_f32 v[34:35], v[26:27], v[102:103]
	s_nop 1
	v_mov_b32_dpp v75, v34 row_ror:1 row_mask:0xf bank_mask:0xf
	v_mov_b32_dpp v38, v34 row_ror:2 row_mask:0xf bank_mask:0xf
	v_mov_b32_dpp v63, v35 row_ror:1 row_mask:0xf bank_mask:0xf
	v_mov_b32_dpp v39, v35 row_ror:2 row_mask:0xf bank_mask:0xf
	v_mov_b32_dpp v77, v36 row_ror:1 row_mask:0xf bank_mask:0xf
	v_mov_b32_dpp v40, v36 row_ror:2 row_mask:0xf bank_mask:0xf
	v_mov_b32_dpp v65, v37 row_ror:1 row_mask:0xf bank_mask:0xf
	v_mov_b32_dpp v41, v37 row_ror:2 row_mask:0xf bank_mask:0xf
	v_pk_mul_f32 v[28:29], v[32:33], v[42:43]
	v_pk_mul_f32 v[26:27], v[30:31], v[102:103]
	s_and_saveexec_b64 s[10:11], s[42:43]
	s_xor_b64 s[10:11], exec, s[10:11]
	s_cbranch_execz .LBB0_61
	v_mov_b32_e32 v30, v37
	v_mov_b32_e32 v31, v81
	s_waitcnt lgkmcnt(1)
	v_pk_mul_f32 v[30:31], v[30:31], v[64:65]
	s_waitcnt lgkmcnt(0)
	v_fma_f32 v32, v69, v41, v73
	v_add_f32_e32 v31, v31, v32
	v_add_f32_e32 v30, v30, v31
	v_mul_f32_e32 v31, 0xbfb8aa3b, v30
	v_exp_f32_e32 v31, v31
	v_mov_b32_e32 v37, v80
	v_add_f32_e32 v31, 1.0, v31
	v_rcp_f32_e32 v31, v31
	s_nop 0
	v_mul_f32_e32 v30, v30, v31
	v_mul_f32_e32 v32, v29, v30
	v_pk_mul_f32 v[30:31], v[36:37], v[76:77]
	v_fma_f32 v29, v68, v40, v72
	v_add_f32_e32 v29, v31, v29
	v_add_f32_e32 v29, v30, v29
	v_mul_f32_e32 v30, 0xbfb8aa3b, v29
	v_exp_f32_e32 v30, v30
	v_fma_f32 v31, v67, v39, v71
	v_add_f32_e32 v30, 1.0, v30
	v_rcp_f32_e32 v30, v30
	s_nop 0
	v_mul_f32_e32 v29, v29, v30
	v_mul_f32_e32 v30, v28, v29
	v_mov_b32_e32 v28, v35
	v_mov_b32_e32 v29, v79
	v_pk_mul_f32 v[28:29], v[28:29], v[62:63]
	v_mov_b32_e32 v35, v78
	v_add_f32_e32 v29, v29, v31
	v_add_f32_e32 v28, v28, v29
	v_mul_f32_e32 v29, 0xbfb8aa3b, v28
	v_exp_f32_e32 v29, v29
	v_fma_f32 v31, v66, v38, v70
	v_add_f32_e32 v29, 1.0, v29
	v_rcp_f32_e32 v29, v29
	s_nop 0
	v_mul_f32_e32 v28, v28, v29
	v_mul_f32_e32 v27, v27, v28
	v_pk_mul_f32 v[28:29], v[34:35], v[74:75]
	s_nop 0
	v_add_f32_e32 v29, v29, v31
	v_add_f32_e32 v28, v28, v29
	v_mul_f32_e32 v29, 0xbfb8aa3b, v28
	v_exp_f32_e32 v29, v29
	s_nop 0
	v_add_f32_e32 v29, 1.0, v29
	v_rcp_f32_e32 v29, v29
	s_nop 0
	v_mul_f32_e32 v28, v28, v29
	v_mul_f32_e32 v26, v26, v28
	v_mov_b64_e32 v[28:29], s[48:49]
	v_mad_i64_i32 v[28:29], s[12:13], v180, s17, v[28:29]
	v_cvt_pk_bf16_f32 v26, v26, v27
	v_cvt_pk_bf16_f32 v27, v30, v32
	v_lshl_add_u64 v[28:29], v[156:157], 1, v[28:29]
	s_nop 1
	v_permlane16_swap_b32_e32 v212, v26
	v_permlane16_swap_b32_e32 v213, v27
	v_mov_b32_e32 v220, v212
	v_mov_b32_e32 v221, v213
	v_mov_b32_e32 v222, v26
	v_mov_b32_e32 v223, v27
	v_add_co_u32_e64 v28, s[98:99], v28, v205
	s_nop 1
	v_addc_co_u32_e64 v29, s[98:99], 0, v29, s[98:99]
	global_store_dwordx4 v[28:29], v[220:223], off

; __device__ __forceinline__ unsigned cvt_pk_bf16(float lo, float hi) { unsigned r; asm volatile("v_cvt_pk_bf16_f32 %0, %1, %2" : "=v"(r) : "v"(lo), "v"(hi)); return r; }
;     __device__ __forceinline__ void operator()(const f32x4 (&acc)[2][2][4][2], const Unit& u, int wr, int wc, int fr, int fq) const {
;     ...
;                     const f32x4 g = acc[ai][1][m][n] * rs[ai][m], v = acc[ai][0][m][n] * rs[ai][m];
;                     f32x4 r1, r2, a;
; #pragma unroll
;                     for (int e = 0; e < 4; ++e) { r1[e] = __shfl(g[e], src1); r2[e] = __shfl(g[e], src2); }
; #pragma unroll
;                     for (int e = 0; e < 4; ++e) {
;                         const float p1 = fr >= 1 ? r1[e] : r1p[e], p2 = fr >= 2 ? r2[e] : r2p[e];
;                         const float gg = b4[e] + w0[e] * p2 + w1[e] * p1 + w2[e] * g[e];
;                         a[e] = gg * __builtin_amdgcn_rcpf(1.f + __expf(-gg)) * v[e];
;                     }
;                     r1p = r1; r2p = r2;
;                     const size_t row = (size_t)(u.pm * BM + ai * HALF + wr * 64 + m * 16 + fr);
;                     if (m == 0 && fr < 2) {
;                         *(f32x4*)(GF + (size_t)(slab * 2 + fr) * FF + cbase) = g; *(f32x4*)(VF + (size_t)(slab * 2 + fr) * FF + cbase) = v;
;                     } else {
;                         typedef unsigned u32x2v __attribute__((ext_vector_type(2)));
;                         u32x2v w; w.x = cvt_pk_bf16(a[0], a[1]); w.y = cvt_pk_bf16(a[2], a[3]);
;                         *(u32x2v*)(ACT + row * FF + cbase) = w;
.LBB0_63:
	s_or_b64 exec, exec, s[10:11]
	s_nop 0
	v_mov_b32_e32 v26, v94
	v_mov_b32_e32 v27, v94
	v_pk_mul_f32 v[24:25], v[24:25], v[26:27]
	s_nop 1
	v_mov_b32_dpp v31, v25 row_ror:1 row_mask:0xf bank_mask:0xf
	v_mov_b32_dpp v35, v25 row_ror:2 row_mask:0xf bank_mask:0xf
	v_mov_b32_e32 v28, v25
	v_mov_b32_e32 v29, v81
	v_mov_b32_dpp v36, v24 row_ror:2 row_mask:0xf bank_mask:0xf
	s_waitcnt lgkmcnt(2)
	v_cndmask_b32_e64 v65, v31, v65, s[40:41]
	s_waitcnt lgkmcnt(1)
	v_cndmask_b32_e64 v25, v41, v35, s[42:43]
	v_pk_mul_f32 v[28:29], v[28:29], v[64:65]
	v_fma_f32 v25, v69, v25, v73
	v_add_f32_e32 v25, v29, v25
	v_add_f32_e32 v28, v28, v25
	v_mul_f32_e32 v25, 0xbfb8aa3b, v28
	v_exp_f32_e32 v25, v25
	v_mov_b32_dpp v29, v24 row_ror:1 row_mask:0xf bank_mask:0xf
	v_pk_mul_f32 v[20:21], v[20:21], v[26:27]
	s_waitcnt lgkmcnt(1)
	v_cndmask_b32_e64 v27, v40, v36, s[42:43]
	v_add_f32_e32 v25, 1.0, v25
	v_rcp_f32_e32 v26, v25
	s_waitcnt lgkmcnt(0)
	v_cndmask_b32_e64 v77, v29, v77, s[40:41]
	v_mov_b32_e32 v25, v80
	v_pk_mul_f32 v[24:25], v[24:25], v[76:77]
	v_fma_f32 v27, v68, v27, v72
	v_add_f32_e32 v25, v25, v27
	v_mov_b32_e32 v95, v94
	v_add_f32_e32 v27, v24, v25
	v_pk_mul_f32 v[22:23], v[22:23], v[94:95]
	v_mul_f32_e32 v24, 0xbfb8aa3b, v27
	s_nop 1
	v_mov_b32_dpp v33, v23 row_ror:1 row_mask:0xf bank_mask:0xf
	v_mov_b32_dpp v34, v23 row_ror:2 row_mask:0xf bank_mask:0xf
	v_exp_f32_e32 v24, v24
	v_mul_f32_e32 v25, v28, v26
	v_mov_b32_dpp v30, v22 row_ror:1 row_mask:0xf bank_mask:0xf
	v_mov_b32_dpp v32, v22 row_ror:2 row_mask:0xf bank_mask:0xf
	v_add_f32_e32 v24, 1.0, v24
	v_mul_f32_e32 v21, v21, v25
	v_rcp_f32_e32 v26, v24
	s_waitcnt lgkmcnt(3)
	v_cndmask_b32_e64 v63, v33, v63, s[40:41]
	v_mov_b32_e32 v24, v23
	v_mov_b32_e32 v25, v79
	s_waitcnt lgkmcnt(2)
	v_cndmask_b32_e64 v23, v39, v34, s[42:43]
	v_pk_mul_f32 v[24:25], v[24:25], v[62:63]
	v_fma_f32 v23, v67, v23, v71
	v_add_f32_e32 v23, v25, v23
	v_add_f32_e32 v24, v24, v23
	v_mul_f32_e32 v23, 0xbfb8aa3b, v24
	v_exp_f32_e32 v25, v23
	s_waitcnt lgkmcnt(1)
	v_cndmask_b32_e64 v75, v30, v75, s[40:41]
	v_mov_b32_e32 v23, v78
	s_waitcnt lgkmcnt(0)
	v_cndmask_b32_e64 v28, v38, v32, s[42:43]
	v_pk_mul_f32 v[22:23], v[22:23], v[74:75]
	v_fma_f32 v28, v66, v28, v70
	v_add_f32_e32 v23, v23, v28
	v_add_f32_e32 v22, v22, v23
	v_mul_f32_e32 v23, 0xbfb8aa3b, v22
	v_exp_f32_e32 v23, v23
	v_add_f32_e32 v25, 1.0, v25
	v_rcp_f32_e32 v25, v25
	v_pk_mul_f32 v[18:19], v[18:19], v[94:95]
	v_add_f32_e32 v23, 1.0, v23
	v_rcp_f32_e32 v23, v23
	v_mul_f32_e32 v24, v24, v25
	v_mul_f32_e32 v26, v27, v26
	v_mul_f32_e32 v19, v19, v24
	v_mul_f32_e32 v22, v22, v23
	v_mul_f32_e32 v18, v18, v22
	v_mul_f32_e32 v20, v20, v26
	v_cvt_pk_bf16_f32 v18, v18, v19
	v_cvt_pk_bf16_f32 v19, v20, v21
	s_nop 1
	v_permlane16_swap_b32_e32 v214, v18
	v_permlane16_swap_b32_e32 v215, v19
	v_mov_b32_e32 v220, v214
	v_mov_b32_e32 v221, v215
	v_mov_b32_e32 v222, v18
	v_mov_b32_e32 v223, v19
	v_add_co_u32_e64 v98, s[98:99], v98, v205
	s_nop 1
	v_addc_co_u32_e64 v99, s[98:99], 0, v99, s[98:99]
	global_store_dwordx4 v[98:99], v[220:223], off
	v_mov_b32_e32 v18, v92
	v_mov_b32_e32 v19, v92
	v_pk_mul_f32 v[16:17], v[16:17], v[18:19]
	s_nop 1
	v_mov_b32_dpp v23, v17 row_ror:1 row_mask:0xf bank_mask:0xf
	v_mov_b32_dpp v27, v17 row_ror:2 row_mask:0xf bank_mask:0xf
	v_mov_b32_e32 v20, v17
	v_mov_b32_e32 v21, v81
	v_mov_b32_dpp v28, v16 row_ror:2 row_mask:0xf bank_mask:0xf
	s_waitcnt lgkmcnt(2)
	v_cndmask_b32_e64 v65, v23, v31, s[40:41]
	s_waitcnt lgkmcnt(1)
	v_cndmask_b32_e64 v17, v35, v27, s[42:43]
	v_pk_mul_f32 v[20:21], v[20:21], v[64:65]
	v_fma_f32 v17, v69, v17, v73
	v_add_f32_e32 v17, v21, v17
	v_add_f32_e32 v20, v20, v17
	v_mul_f32_e32 v17, 0xbfb8aa3b, v20
	v_exp_f32_e32 v17, v17
	v_mov_b32_dpp v21, v16 row_ror:1 row_mask:0xf bank_mask:0xf
	v_pk_mul_f32 v[12:13], v[12:13], v[18:19]
	s_waitcnt lgkmcnt(1)
	v_cndmask_b32_e64 v19, v36, v28, s[42:43]
	v_add_f32_e32 v17, 1.0, v17
	v_rcp_f32_e32 v18, v17
	s_waitcnt lgkmcnt(0)
	v_cndmask_b32_e64 v77, v21, v29, s[40:41]
	v_mov_b32_e32 v17, v80
	v_pk_mul_f32 v[16:17], v[16:17], v[76:77]
	v_fma_f32 v19, v68, v19, v72
	v_add_f32_e32 v17, v17, v19
	v_mov_b32_e32 v93, v92
	v_add_f32_e32 v19, v16, v17
	v_pk_mul_f32 v[14:15], v[14:15], v[92:93]
	v_mul_f32_e32 v16, 0xbfb8aa3b, v19
	s_nop 1
	v_mov_b32_dpp v25, v15 row_ror:1 row_mask:0xf bank_mask:0xf
	v_mov_b32_dpp v26, v15 row_ror:2 row_mask:0xf bank_mask:0xf
	v_exp_f32_e32 v16, v16
	v_mul_f32_e32 v17, v20, v18
	v_mov_b32_dpp v22, v14 row_ror:1 row_mask:0xf bank_mask:0xf
	v_mov_b32_dpp v24, v14 row_ror:2 row_mask:0xf bank_mask:0xf
	v_add_f32_e32 v16, 1.0, v16
	v_mul_f32_e32 v13, v13, v17
	v_rcp_f32_e32 v18, v16
	s_waitcnt lgkmcnt(3)
; __device__ __forceinline__ unsigned cvt_pk_bf16(float lo, float hi) { unsigned r; asm volatile("v_cvt_pk_bf16_f32 %0, %1, %2" : "=v"(r) : "v"(lo), "v"(hi)); return r; }
;     __device__ __forceinline__ void operator()(const f32x4 (&acc)[2][2][4][2], const Unit& u, int wr, int wc, int fr, int fq) const {
;     ...
;                     const f32x4 g = acc[ai][1][m][n] * rs[ai][m], v = acc[ai][0][m][n] * rs[ai][m];
;                     f32x4 r1, r2, a;
; #pragma unroll
;                     for (int e = 0; e < 4; ++e) { r1[e] = __shfl(g[e], src1); r2[e] = __shfl(g[e], src2); }
; #pragma unroll
;                     for (int e = 0; e < 4; ++e) {
;                         const float p1 = fr >= 1 ? r1[e] : r1p[e], p2 = fr >= 2 ? r2[e] : r2p[e];
;                         const float gg = b4[e] + w0[e] * p2 + w1[e] * p1 + w2[e] * g[e];
;                         a[e] = gg * __builtin_amdgcn_rcpf(1.f + __expf(-gg)) * v[e];
;                     }
;                     r1p = r1; r2p = r2;
;                     const size_t row = (size_t)(u.pm * BM + ai * HALF + wr * 64 + m * 16 + fr);
;                     if (m == 0 && fr < 2) {
;                         *(f32x4*)(GF + (size_t)(slab * 2 + fr) * FF + cbase) = g; *(f32x4*)(VF + (size_t)(slab * 2 + fr) * FF + cbase) = v;
;                     } else {
;                         typedef unsigned u32x2v __attribute__((ext_vector_type(2)));
;                         u32x2v w; w.x = cvt_pk_bf16(a[0], a[1]); w.y = cvt_pk_bf16(a[2], a[3]);
;                         *(u32x2v*)(ACT + row * FF + cbase) = w;
;                     }
;                     if (m == 3 && fr >= 14) *(f32x4*)(GL + (size_t)(slab * 2 + fr - 14) * FF + cbase) = g;
	v_cndmask_b32_e64 v63, v25, v33, s[40:41]
	v_mov_b32_e32 v16, v15
	v_mov_b32_e32 v17, v79
	s_waitcnt lgkmcnt(2)
	v_cndmask_b32_e64 v15, v34, v26, s[42:43]
	v_pk_mul_f32 v[16:17], v[16:17], v[62:63]
	v_fma_f32 v15, v67, v15, v71
	v_add_f32_e32 v15, v17, v15
	v_add_f32_e32 v16, v16, v15
	v_mul_f32_e32 v15, 0xbfb8aa3b, v16
	v_exp_f32_e32 v17, v15
	s_waitcnt lgkmcnt(1)
	v_cndmask_b32_e64 v75, v22, v30, s[40:41]
	v_mov_b32_e32 v15, v78
	s_waitcnt lgkmcnt(0)
	v_cndmask_b32_e64 v20, v32, v24, s[42:43]
	v_pk_mul_f32 v[14:15], v[14:15], v[74:75]
	v_fma_f32 v20, v66, v20, v70
	v_add_f32_e32 v15, v15, v20
	v_add_f32_e32 v14, v14, v15
	v_mul_f32_e32 v15, 0xbfb8aa3b, v14
	v_exp_f32_e32 v15, v15
	v_add_f32_e32 v17, 1.0, v17
	v_rcp_f32_e32 v17, v17
	v_pk_mul_f32 v[10:11], v[10:11], v[92:93]
	v_add_f32_e32 v15, 1.0, v15
	v_rcp_f32_e32 v15, v15
	v_mul_f32_e32 v16, v16, v17
	v_mul_f32_e32 v18, v19, v18
	v_mul_f32_e32 v11, v11, v16
	v_mul_f32_e32 v14, v14, v15
	v_mul_f32_e32 v10, v10, v14
	v_mul_f32_e32 v12, v12, v18
	v_cvt_pk_bf16_f32 v10, v10, v11
	v_cvt_pk_bf16_f32 v11, v12, v13
	s_nop 1
	v_permlane16_swap_b32_e32 v216, v10
	v_permlane16_swap_b32_e32 v217, v11
	v_mov_b32_e32 v220, v216
	v_mov_b32_e32 v221, v217
	v_mov_b32_e32 v222, v10
	v_mov_b32_e32 v223, v11
	v_add_co_u32_e64 v96, s[98:99], v96, v205
	s_nop 1
	v_addc_co_u32_e64 v97, s[98:99], 0, v97, s[98:99]
	global_store_dwordx4 v[96:97], v[220:223], off
	v_mov_b32_e32 v10, v90
	v_mov_b32_e32 v11, v90
	v_pk_mul_f32 v[8:9], v[8:9], v[10:11]
	s_nop 1
	v_mov_b32_dpp v12, v9 row_ror:1 row_mask:0xf bank_mask:0xf
	v_mov_b32_dpp v18, v9 row_ror:2 row_mask:0xf bank_mask:0xf
	v_mov_b32_e32 v13, v81
	v_mov_b32_dpp v19, v8 row_ror:2 row_mask:0xf bank_mask:0xf
	v_pk_mul_f32 v[4:5], v[4:5], v[10:11]
	s_waitcnt lgkmcnt(2)
	v_cndmask_b32_e64 v65, v12, v23, s[40:41]
	v_mov_b32_e32 v12, v9
	s_waitcnt lgkmcnt(1)
	v_cndmask_b32_e64 v18, v27, v18, s[42:43]
	v_pk_mul_f32 v[12:13], v[12:13], v[64:65]
	v_fma_f32 v18, v69, v18, v73
	v_add_f32_e32 v13, v13, v18
	v_add_f32_e32 v12, v12, v13
	v_mul_f32_e32 v13, 0xbfb8aa3b, v12
	v_exp_f32_e32 v13, v13
	v_mov_b32_dpp v18, v8 row_ror:1 row_mask:0xf bank_mask:0xf
	v_mov_b32_e32 v11, v80
	v_mov_b32_e32 v91, v90
	v_add_f32_e32 v10, 1.0, v13
	v_rcp_f32_e32 v13, v10
	s_waitcnt lgkmcnt(0)
	v_cndmask_b32_e64 v77, v18, v21, s[40:41]
	v_mov_b32_e32 v10, v8
	v_cndmask_b32_e64 v18, v28, v19, s[42:43]
	v_pk_mul_f32 v[10:11], v[10:11], v[76:77]
	v_fma_f32 v18, v68, v18, v72
	v_add_f32_e32 v11, v11, v18
	v_add_f32_e32 v18, v10, v11
	v_pk_mul_f32 v[6:7], v[6:7], v[90:91]
	v_mul_f32_e32 v10, 0xbfb8aa3b, v18
	s_nop 1
	v_mov_b32_dpp v16, v7 row_ror:1 row_mask:0xf bank_mask:0xf
	v_mov_b32_dpp v17, v7 row_ror:2 row_mask:0xf bank_mask:0xf
	v_exp_f32_e32 v10, v10
	v_mul_f32_e32 v11, v12, v13
	v_mov_b32_dpp v14, v6 row_ror:1 row_mask:0xf bank_mask:0xf
	v_mov_b32_dpp v15, v6 row_ror:2 row_mask:0xf bank_mask:0xf
	v_add_f32_e32 v10, 1.0, v10
	v_mul_f32_e32 v5, v5, v11
	v_rcp_f32_e32 v12, v10
	s_waitcnt lgkmcnt(3)
	v_cndmask_b32_e64 v63, v16, v25, s[40:41]
	v_mov_b32_e32 v10, v7
	v_mov_b32_e32 v11, v79
	s_waitcnt lgkmcnt(2)
	v_cndmask_b32_e64 v13, v26, v17, s[42:43]
	v_pk_mul_f32 v[10:11], v[10:11], v[62:63]
	v_fma_f32 v13, v67, v13, v71
	v_add_f32_e32 v11, v11, v13
	v_add_f32_e32 v13, v10, v11
	v_mul_f32_e32 v10, 0xbfb8aa3b, v13
	v_exp_f32_e32 v16, v10
	s_waitcnt lgkmcnt(1)
	v_cndmask_b32_e64 v75, v14, v22, s[40:41]
	v_mov_b32_e32 v10, v6
	v_mov_b32_e32 v11, v78
	s_waitcnt lgkmcnt(0)
	v_cndmask_b32_e64 v14, v24, v15, s[42:43]
	v_pk_mul_f32 v[10:11], v[10:11], v[74:75]
	v_fmac_f32_e32 v70, v66, v14
	v_add_f32_e32 v11, v11, v70
	v_add_f32_e32 v10, v10, v11
	v_mul_f32_e32 v11, 0xbfb8aa3b, v10
	v_exp_f32_e32 v11, v11
	v_add_f32_e32 v14, 1.0, v16
	v_rcp_f32_e32 v14, v14
	v_mul_f32_e32 v12, v18, v12
	v_add_f32_e32 v11, 1.0, v11
	v_rcp_f32_e32 v11, v11
	v_pk_mul_f32 v[2:3], v[2:3], v[90:91]
	v_mul_f32_e32 v4, v4, v12
	v_mul_f32_e32 v12, v13, v14
	v_mul_f32_e32 v10, v10, v11
	v_mul_f32_e32 v3, v3, v12
	v_mul_f32_e32 v2, v2, v10
	v_cvt_pk_bf16_f32 v2, v2, v3
	v_cvt_pk_bf16_f32 v3, v4, v5
	s_nop 1
	v_permlane16_swap_b32_e32 v218, v2
	v_permlane16_swap_b32_e32 v219, v3
	v_mov_b32_e32 v220, v218
	v_mov_b32_e32 v221, v219
	v_mov_b32_e32 v222, v2
	v_mov_b32_e32 v223, v3
	v_add_co_u32_e64 v88, s[98:99], v88, v205
	s_nop 1
	v_addc_co_u32_e64 v89, s[98:99], 0, v89, s[98:99]
	global_store_dwordx4 v[88:89], v[220:223], off
	s_and_saveexec_b64 s[10:11], s[44:45]
	s_cbranch_execz .LBB0_65
	global_store_dwordx4 v[86:87], v[6:9], off offset:64
